# LDS-free cross-lane reduction: 26 ds_swizzle SWAP16 + lgkm wait sites (RESIDN/RESID epilogue row sums, NORM/NORMKV wave_sum) replaced by v_mov + v_permlane16_swap
# speedup vs baseline: 1.0097x; 1.0097x over previous
.LBB0_458:
	s_lshl_b32 s0, s52, 8
	v_mov_b32_e32 v254, v249
	v_mov_b32_e32 v250, v243
	s_or_b32 s0, s0, s31
	s_lshl_b32 s83, s40, 8
	v_lshl_add_u32 v216, v254, 3, s0
	s_ashr_i32 s0, s40, 5
	s_mul_hi_i32 s1, s0, 0x9000
	s_mul_i32 s0, s0, 0x9000
	s_add_u32 s0, s20, s0
	s_addc_u32 s1, s21, s1
	v_ashrrev_i32_e32 v217, 31, v216
	v_lshl_add_u64 v[138:139], v[216:217], 2, s[0:1]
	global_load_dwordx2 v[232:233], v[138:139], off offset:16
	global_load_dwordx2 v[230:231], v[138:139], off offset:24
	global_load_dwordx2 v[240:241], v[138:139], off
	global_load_dwordx2 v[238:239], v[138:139], off offset:8
	global_load_dwordx2 v[228:229], v[138:139], off offset:528
	global_load_dwordx2 v[226:227], v[138:139], off offset:536
	global_load_dwordx2 v[236:237], v[138:139], off offset:512
	global_load_dwordx2 v[234:235], v[138:139], off offset:520
	s_mov_b32 s25, s24
	v_add_u32_e32 v253, s30, v250
	v_add_u32_e32 v220, s83, v253
	v_ashrrev_i32_e32 v221, 31, v220
	v_add_u32_e32 v218, 16, v220
	v_ashrrev_i32_e32 v219, 31, v218
	v_add_u32_e32 v214, 32, v220
	v_ashrrev_i32_e32 v215, 31, v214
	v_add_u32_e32 v212, 48, v220
	v_ashrrev_i32_e32 v213, 31, v212
	v_add_u32_e32 v210, 0x80, v220
	v_ashrrev_i32_e32 v211, 31, v210
	v_add_u32_e32 v208, 0x90, v220
	v_ashrrev_i32_e32 v209, 31, v208
	v_add_u32_e32 v206, 0xa0, v220
	v_add_u32_e32 v204, 0xb0, v220
	v_ashrrev_i32_e32 v207, 31, v206
	v_ashrrev_i32_e32 v205, 31, v204
	v_cmp_eq_u32_e32 vcc, 0, v254
	v_readlane_b32 s0, v255, 19
	v_readlane_b32 s1, v255, 20
	v_lshlrev_b64 v[122:123], 11, v[220:221]
	v_lshl_add_u64 v[126:127], v[216:217], 1, s[0:1]
	v_lshl_add_u64 v[122:123], v[126:127], 0, v[122:123]
	global_load_dwordx4 v[190:193], v[122:123], off
	global_load_dwordx4 v[186:189], v[122:123], off offset:256
	v_lshlrev_b64 v[122:123], 11, v[218:219]
	v_lshl_add_u64 v[122:123], v[126:127], 0, v[122:123]
	global_load_dwordx4 v[182:185], v[122:123], off
	global_load_dwordx4 v[178:181], v[122:123], off offset:256
	v_lshlrev_b64 v[122:123], 11, v[214:215]
	v_lshl_add_u64 v[122:123], v[126:127], 0, v[122:123]
	global_load_dwordx4 v[174:177], v[122:123], off
	global_load_dwordx4 v[170:173], v[122:123], off offset:256
	v_lshlrev_b64 v[122:123], 11, v[212:213]
	v_lshl_add_u64 v[122:123], v[126:127], 0, v[122:123]
	global_load_dwordx4 v[166:169], v[122:123], off
	global_load_dwordx4 v[162:165], v[122:123], off offset:256
	v_lshlrev_b64 v[122:123], 11, v[210:211]
	v_lshl_add_u64 v[122:123], v[126:127], 0, v[122:123]
	global_load_dwordx4 v[158:161], v[122:123], off
	global_load_dwordx4 v[154:157], v[122:123], off offset:256
	v_lshlrev_b64 v[122:123], 11, v[208:209]
	v_lshl_add_u64 v[122:123], v[126:127], 0, v[122:123]
	global_load_dwordx4 v[150:153], v[122:123], off
	global_load_dwordx4 v[146:149], v[122:123], off offset:256
	v_lshlrev_b64 v[122:123], 11, v[206:207]
	v_lshlrev_b64 v[128:129], 11, v[204:205]
	v_lshl_add_u64 v[122:123], v[126:127], 0, v[122:123]
	v_lshl_add_u64 v[126:127], v[126:127], 0, v[128:129]
	global_load_dwordx4 v[138:141], v[122:123], off
	s_nop 0
	global_load_dwordx4 v[122:125], v[122:123], off offset:256
	s_nop 0
	global_load_dwordx4 v[142:145], v[126:127], off
	s_nop 0
	global_load_dwordx4 v[126:129], v[126:127], off offset:256
	v_readlane_b32 s0, v255, 42
	v_readlane_b32 s1, v255, 43
	s_waitcnt vmcnt(16)
	v_pk_mul_f32 v[230:231], s[24:25], v[230:231]
	v_pk_mul_f32 v[238:239], v[238:239], s[24:25]
	v_pk_mul_f32 v[240:241], v[240:241], s[0:1]
	v_pk_mul_f32 v[232:233], s[0:1], v[232:233]
	v_pk_mul_f32 v[228:229], s[0:1], v[228:229]
	v_pk_mul_f32 v[236:237], s[0:1], v[236:237]
	v_pk_mul_f32 v[234:235], s[24:25], v[234:235]
	v_pk_mul_f32 v[226:227], s[24:25], v[226:227]
	s_waitcnt vmcnt(15)
	v_cvt_f32_f16_e32 v222, v190
	v_cvt_f32_f16_sdwa v223, v190 dst_sel:DWORD dst_unused:UNUSED_PAD src0_sel:WORD_1
	v_cvt_f32_f16_e32 v190, v191
	v_cvt_f32_f16_sdwa v191, v191 dst_sel:DWORD dst_unused:UNUSED_PAD src0_sel:WORD_1
	v_pk_fma_f32 v[134:135], v[134:135], v[240:241], v[222:223]
	v_pk_fma_f32 v[136:137], v[136:137], v[238:239], v[190:191]
	v_cvt_f32_f16_e32 v190, v192
	v_cvt_f32_f16_sdwa v191, v192 dst_sel:DWORD dst_unused:UNUSED_PAD src0_sel:WORD_1
	v_cvt_f32_f16_e32 v192, v193
	v_cvt_f32_f16_sdwa v193, v193 dst_sel:DWORD dst_unused:UNUSED_PAD src0_sel:WORD_1
	v_pk_fma_f32 v[130:131], v[130:131], v[232:233], v[190:191]
	s_waitcnt vmcnt(14)
	v_cvt_f32_f16_e32 v190, v186
	v_cvt_f32_f16_sdwa v191, v186 dst_sel:DWORD dst_unused:UNUSED_PAD src0_sel:WORD_1
	v_cvt_f32_f16_e32 v186, v187
	v_cvt_f32_f16_sdwa v187, v187 dst_sel:DWORD dst_unused:UNUSED_PAD src0_sel:WORD_1
	v_pk_fma_f32 v[132:133], v[132:133], v[230:231], v[192:193]
	v_pk_fma_f32 v[118:119], v[118:119], v[236:237], v[190:191]
	v_pk_fma_f32 v[120:121], v[120:121], v[234:235], v[186:187]
	v_cvt_f32_f16_e32 v186, v188
	v_cvt_f32_f16_sdwa v187, v188 dst_sel:DWORD dst_unused:UNUSED_PAD src0_sel:WORD_1
	v_cvt_f32_f16_e32 v188, v189
	v_cvt_f32_f16_sdwa v189, v189 dst_sel:DWORD dst_unused:UNUSED_PAD src0_sel:WORD_1
	v_pk_fma_f32 v[114:115], v[114:115], v[228:229], v[186:187]
	v_mul_f32_e32 v186, v135, v135
	v_mul_f32_e32 v187, v137, v137
	v_fmac_f32_e32 v186, v134, v134
	v_fmac_f32_e32 v187, v136, v136
	v_pk_fma_f32 v[116:117], v[116:117], v[226:227], v[188:189]
	v_add_f32_e32 v186, v186, v187
	v_mul_f32_e32 v187, v131, v131
	v_mul_f32_e32 v188, v133, v133
	v_fmac_f32_e32 v187, v130, v130
	v_fmac_f32_e32 v188, v132, v132
	v_add_f32_e32 v187, v187, v188
	v_add_f32_e32 v186, v186, v187
	v_mul_f32_e32 v187, v119, v119
	v_mul_f32_e32 v188, v121, v121
	v_fmac_f32_e32 v187, v118, v118
	v_fmac_f32_e32 v188, v120, v120
	v_add_f32_e32 v187, v187, v188
	v_add_f32_e32 v186, v186, v187
	v_mul_f32_e32 v187, v115, v115
	v_mul_f32_e32 v188, v117, v117
	v_fmac_f32_e32 v187, v114, v114
	v_fmac_f32_e32 v188, v116, v116
	v_add_f32_e32 v187, v187, v188
	v_add_f32_e32 v186, v187, v186
	v_mov_b32_e32 v187, v186
	s_nop 1
	v_permlane16_swap_b32_e32 v187, v186
	s_waitcnt lgkmcnt(0)
	v_add_f32_e32 v187, v186, v187
	v_mov_b32_e32 v188, v187
	s_nop 1
	v_permlane32_swap_b32_e32 v187, v188
	v_lshl_add_u32 v186, v250, 4, s74
	s_and_saveexec_b64 s[0:1], vcc
	v_add_f32_e32 v187, v187, v188
	ds_write_b32 v186, v187
	s_or_b64 exec, exec, s[0:1]
	s_waitcnt vmcnt(13)
	v_cvt_f32_f16_sdwa v189, v182 dst_sel:DWORD dst_unused:UNUSED_PAD src0_sel:WORD_1
	v_cvt_f32_f16_e32 v188, v182
	v_cvt_f32_f16_sdwa v191, v183 dst_sel:DWORD dst_unused:UNUSED_PAD src0_sel:WORD_1
	v_cvt_f32_f16_e32 v190, v183
	v_cvt_f32_f16_sdwa v183, v184 dst_sel:DWORD dst_unused:UNUSED_PAD src0_sel:WORD_1
	v_cvt_f32_f16_e32 v182, v184
	v_pk_fma_f32 v[110:111], v[110:111], v[240:241], v[188:189]
	v_cvt_f32_f16_sdwa v189, v185 dst_sel:DWORD dst_unused:UNUSED_PAD src0_sel:WORD_1
	v_cvt_f32_f16_e32 v188, v185
	v_pk_fma_f32 v[106:107], v[106:107], v[232:233], v[182:183]
	s_waitcnt vmcnt(12)
	v_cvt_f32_f16_sdwa v183, v178 dst_sel:DWORD dst_unused:UNUSED_PAD src0_sel:WORD_1
	v_cvt_f32_f16_e32 v182, v178
	v_cvt_f32_f16_sdwa v185, v179 dst_sel:DWORD dst_unused:UNUSED_PAD src0_sel:WORD_1
	v_cvt_f32_f16_e32 v184, v179
	v_cvt_f32_f16_sdwa v179, v180 dst_sel:DWORD dst_unused:UNUSED_PAD src0_sel:WORD_1
	v_cvt_f32_f16_e32 v178, v180
	v_pk_fma_f32 v[112:113], v[112:113], v[238:239], v[190:191]
	v_pk_fma_f32 v[108:109], v[108:109], v[230:231], v[188:189]
	v_pk_fma_f32 v[102:103], v[102:103], v[236:237], v[182:183]
	v_pk_fma_f32 v[98:99], v[98:99], v[228:229], v[178:179]
	v_mul_f32_e32 v178, v111, v111
	v_mul_f32_e32 v179, v113, v113
	v_fmac_f32_e32 v178, v110, v110
	v_fmac_f32_e32 v179, v112, v112
	v_add_f32_e32 v178, v178, v179
	v_mul_f32_e32 v179, v107, v107
	v_mul_f32_e32 v180, v109, v109
	v_cvt_f32_f16_sdwa v183, v181 dst_sel:DWORD dst_unused:UNUSED_PAD src0_sel:WORD_1
	v_cvt_f32_f16_e32 v182, v181
	v_fmac_f32_e32 v179, v106, v106
	v_fmac_f32_e32 v180, v108, v108
	v_pk_fma_f32 v[104:105], v[104:105], v[234:235], v[184:185]
	v_add_f32_e32 v179, v179, v180
	v_add_f32_e32 v178, v178, v179
	v_mul_f32_e32 v179, v103, v103
	v_mul_f32_e32 v180, v105, v105
	v_fmac_f32_e32 v179, v102, v102
	v_fmac_f32_e32 v180, v104, v104
	v_pk_fma_f32 v[100:101], v[100:101], v[226:227], v[182:183]
	v_add_f32_e32 v179, v179, v180
	v_add_f32_e32 v178, v178, v179
	v_mul_f32_e32 v179, v99, v99
	v_mul_f32_e32 v180, v101, v101
	v_fmac_f32_e32 v179, v98, v98
	v_fmac_f32_e32 v180, v100, v100
	v_add_f32_e32 v179, v179, v180
	v_add_f32_e32 v178, v179, v178
	v_mov_b32_e32 v179, v178
	s_nop 1
	v_permlane16_swap_b32_e32 v179, v178
	s_waitcnt lgkmcnt(0)
	v_add_f32_e32 v178, v178, v179
	v_mov_b32_e32 v179, v178
	s_nop 1
	v_permlane32_swap_b32_e32 v178, v179
	s_and_saveexec_b64 s[0:1], vcc
	v_add_f32_e32 v178, v178, v179
	ds_write_b32 v186, v178 offset:256
	s_or_b64 exec, exec, s[0:1]
	s_waitcnt vmcnt(11)
	v_cvt_f32_f16_sdwa v179, v174 dst_sel:DWORD dst_unused:UNUSED_PAD src0_sel:WORD_1
	v_cvt_f32_f16_e32 v178, v174
	v_cvt_f32_f16_sdwa v181, v175 dst_sel:DWORD dst_unused:UNUSED_PAD src0_sel:WORD_1
	v_cvt_f32_f16_e32 v180, v175
	v_cvt_f32_f16_sdwa v175, v176 dst_sel:DWORD dst_unused:UNUSED_PAD src0_sel:WORD_1
	v_cvt_f32_f16_e32 v174, v176
	v_pk_fma_f32 v[94:95], v[94:95], v[240:241], v[178:179]
	v_cvt_f32_f16_sdwa v179, v177 dst_sel:DWORD dst_unused:UNUSED_PAD src0_sel:WORD_1
	v_cvt_f32_f16_e32 v178, v177
	v_pk_fma_f32 v[90:91], v[90:91], v[232:233], v[174:175]
	s_waitcnt vmcnt(10)
	v_cvt_f32_f16_sdwa v175, v170 dst_sel:DWORD dst_unused:UNUSED_PAD src0_sel:WORD_1
	v_cvt_f32_f16_e32 v174, v170
	v_cvt_f32_f16_sdwa v177, v171 dst_sel:DWORD dst_unused:UNUSED_PAD src0_sel:WORD_1
	v_cvt_f32_f16_e32 v176, v171
	v_cvt_f32_f16_sdwa v171, v172 dst_sel:DWORD dst_unused:UNUSED_PAD src0_sel:WORD_1
	v_cvt_f32_f16_e32 v170, v172
	v_pk_fma_f32 v[96:97], v[96:97], v[238:239], v[180:181]
	v_pk_fma_f32 v[92:93], v[92:93], v[230:231], v[178:179]
	v_pk_fma_f32 v[86:87], v[86:87], v[236:237], v[174:175]
	v_pk_fma_f32 v[82:83], v[82:83], v[228:229], v[170:171]
	v_mul_f32_e32 v170, v95, v95
	v_mul_f32_e32 v171, v97, v97
	v_fmac_f32_e32 v170, v94, v94
	v_fmac_f32_e32 v171, v96, v96
	v_add_f32_e32 v170, v170, v171
	v_mul_f32_e32 v171, v91, v91
	v_mul_f32_e32 v172, v93, v93
	v_cvt_f32_f16_sdwa v175, v173 dst_sel:DWORD dst_unused:UNUSED_PAD src0_sel:WORD_1
	v_cvt_f32_f16_e32 v174, v173
	v_fmac_f32_e32 v171, v90, v90
	v_fmac_f32_e32 v172, v92, v92
	v_pk_fma_f32 v[88:89], v[88:89], v[234:235], v[176:177]
	v_add_f32_e32 v171, v171, v172
	v_add_f32_e32 v170, v170, v171
	v_mul_f32_e32 v171, v87, v87
	v_mul_f32_e32 v172, v89, v89
	v_fmac_f32_e32 v171, v86, v86
	v_fmac_f32_e32 v172, v88, v88
	v_pk_fma_f32 v[84:85], v[84:85], v[226:227], v[174:175]
	v_add_f32_e32 v171, v171, v172
	v_add_f32_e32 v170, v170, v171
	v_mul_f32_e32 v171, v83, v83
	v_mul_f32_e32 v172, v85, v85
	v_fmac_f32_e32 v171, v82, v82
	v_fmac_f32_e32 v172, v84, v84
	v_add_f32_e32 v171, v171, v172
	v_add_f32_e32 v170, v171, v170
	v_mov_b32_e32 v171, v170
	s_nop 1
	v_permlane16_swap_b32_e32 v171, v170
	s_waitcnt lgkmcnt(0)
	v_add_f32_e32 v170, v170, v171
	v_mov_b32_e32 v171, v170
	s_nop 1
	v_permlane32_swap_b32_e32 v170, v171
	s_and_saveexec_b64 s[0:1], vcc
	v_add_f32_e32 v170, v170, v171
	ds_write_b32 v186, v170 offset:512
	s_or_b64 exec, exec, s[0:1]
	s_waitcnt vmcnt(9)
	v_cvt_f32_f16_sdwa v171, v166 dst_sel:DWORD dst_unused:UNUSED_PAD src0_sel:WORD_1
	v_cvt_f32_f16_e32 v170, v166
	v_cvt_f32_f16_sdwa v173, v167 dst_sel:DWORD dst_unused:UNUSED_PAD src0_sel:WORD_1
	v_cvt_f32_f16_e32 v172, v167
	v_cvt_f32_f16_sdwa v167, v168 dst_sel:DWORD dst_unused:UNUSED_PAD src0_sel:WORD_1
	v_cvt_f32_f16_e32 v166, v168
	v_pk_fma_f32 v[78:79], v[78:79], v[240:241], v[170:171]
	v_cvt_f32_f16_sdwa v171, v169 dst_sel:DWORD dst_unused:UNUSED_PAD src0_sel:WORD_1
	v_cvt_f32_f16_e32 v170, v169
	v_pk_fma_f32 v[74:75], v[74:75], v[232:233], v[166:167]
	s_waitcnt vmcnt(8)
	v_cvt_f32_f16_sdwa v167, v162 dst_sel:DWORD dst_unused:UNUSED_PAD src0_sel:WORD_1
	v_cvt_f32_f16_e32 v166, v162
	v_cvt_f32_f16_sdwa v169, v163 dst_sel:DWORD dst_unused:UNUSED_PAD src0_sel:WORD_1
	v_cvt_f32_f16_e32 v168, v163
	v_cvt_f32_f16_sdwa v163, v164 dst_sel:DWORD dst_unused:UNUSED_PAD src0_sel:WORD_1
	v_cvt_f32_f16_e32 v162, v164
	v_pk_fma_f32 v[80:81], v[80:81], v[238:239], v[172:173]
	v_pk_fma_f32 v[76:77], v[76:77], v[230:231], v[170:171]
	v_pk_fma_f32 v[70:71], v[70:71], v[236:237], v[166:167]
	v_pk_fma_f32 v[66:67], v[66:67], v[228:229], v[162:163]
	v_mul_f32_e32 v162, v79, v79
	v_mul_f32_e32 v163, v81, v81
	v_fmac_f32_e32 v162, v78, v78
	v_fmac_f32_e32 v163, v80, v80
	v_add_f32_e32 v162, v162, v163
	v_mul_f32_e32 v163, v75, v75
	v_mul_f32_e32 v164, v77, v77
	v_cvt_f32_f16_sdwa v167, v165 dst_sel:DWORD dst_unused:UNUSED_PAD src0_sel:WORD_1
	v_cvt_f32_f16_e32 v166, v165
	v_fmac_f32_e32 v163, v74, v74
	v_fmac_f32_e32 v164, v76, v76
	v_pk_fma_f32 v[72:73], v[72:73], v[234:235], v[168:169]
	v_add_f32_e32 v163, v163, v164
	v_add_f32_e32 v162, v162, v163
	v_mul_f32_e32 v163, v71, v71
	v_mul_f32_e32 v164, v73, v73
	v_fmac_f32_e32 v163, v70, v70
	v_fmac_f32_e32 v164, v72, v72
	v_pk_fma_f32 v[68:69], v[68:69], v[226:227], v[166:167]
	v_add_f32_e32 v163, v163, v164
	v_add_f32_e32 v162, v162, v163
	v_mul_f32_e32 v163, v67, v67
	v_mul_f32_e32 v164, v69, v69
	v_fmac_f32_e32 v163, v66, v66
	v_fmac_f32_e32 v164, v68, v68
	v_add_f32_e32 v163, v163, v164
	v_add_f32_e32 v162, v163, v162
	v_mov_b32_e32 v163, v162
	s_nop 1
	v_permlane16_swap_b32_e32 v163, v162
	s_waitcnt lgkmcnt(0)
	v_add_f32_e32 v162, v162, v163
	v_mov_b32_e32 v163, v162
	s_nop 1
	v_permlane32_swap_b32_e32 v162, v163
	s_and_saveexec_b64 s[0:1], vcc
	v_add_f32_e32 v162, v162, v163
	ds_write_b32 v186, v162 offset:768
	s_or_b64 exec, exec, s[0:1]
	s_waitcnt vmcnt(7)
	v_cvt_f32_f16_sdwa v163, v158 dst_sel:DWORD dst_unused:UNUSED_PAD src0_sel:WORD_1
	v_cvt_f32_f16_e32 v162, v158
	v_cvt_f32_f16_sdwa v165, v159 dst_sel:DWORD dst_unused:UNUSED_PAD src0_sel:WORD_1
	v_cvt_f32_f16_e32 v164, v159
	v_cvt_f32_f16_sdwa v159, v160 dst_sel:DWORD dst_unused:UNUSED_PAD src0_sel:WORD_1
	v_cvt_f32_f16_e32 v158, v160
	v_pk_fma_f32 v[62:63], v[62:63], v[240:241], v[162:163]
	v_cvt_f32_f16_sdwa v163, v161 dst_sel:DWORD dst_unused:UNUSED_PAD src0_sel:WORD_1
	v_cvt_f32_f16_e32 v162, v161
	v_pk_fma_f32 v[58:59], v[58:59], v[232:233], v[158:159]
	s_waitcnt vmcnt(6)
	v_cvt_f32_f16_sdwa v159, v154 dst_sel:DWORD dst_unused:UNUSED_PAD src0_sel:WORD_1
	v_cvt_f32_f16_e32 v158, v154
	v_cvt_f32_f16_sdwa v161, v155 dst_sel:DWORD dst_unused:UNUSED_PAD src0_sel:WORD_1
	v_cvt_f32_f16_e32 v160, v155
	v_cvt_f32_f16_sdwa v155, v156 dst_sel:DWORD dst_unused:UNUSED_PAD src0_sel:WORD_1
	v_cvt_f32_f16_e32 v154, v156
	v_pk_fma_f32 v[64:65], v[64:65], v[238:239], v[164:165]
	v_pk_fma_f32 v[60:61], v[60:61], v[230:231], v[162:163]
	v_pk_fma_f32 v[54:55], v[54:55], v[236:237], v[158:159]
	v_pk_fma_f32 v[50:51], v[50:51], v[228:229], v[154:155]
	v_mul_f32_e32 v154, v63, v63
	v_mul_f32_e32 v155, v65, v65
	v_fmac_f32_e32 v154, v62, v62
	v_fmac_f32_e32 v155, v64, v64
	v_add_f32_e32 v154, v154, v155
	v_mul_f32_e32 v155, v59, v59
	v_mul_f32_e32 v156, v61, v61
	v_cvt_f32_f16_sdwa v159, v157 dst_sel:DWORD dst_unused:UNUSED_PAD src0_sel:WORD_1
	v_cvt_f32_f16_e32 v158, v157
	v_fmac_f32_e32 v155, v58, v58
	v_fmac_f32_e32 v156, v60, v60
	v_pk_fma_f32 v[56:57], v[56:57], v[234:235], v[160:161]
	v_add_f32_e32 v155, v155, v156
	v_add_f32_e32 v154, v154, v155
	v_mul_f32_e32 v155, v55, v55
	v_mul_f32_e32 v156, v57, v57
	v_fmac_f32_e32 v155, v54, v54
	v_fmac_f32_e32 v156, v56, v56
	v_pk_fma_f32 v[52:53], v[52:53], v[226:227], v[158:159]
	v_add_f32_e32 v155, v155, v156
	v_add_f32_e32 v154, v154, v155
	v_mul_f32_e32 v155, v51, v51
	v_mul_f32_e32 v156, v53, v53
	v_fmac_f32_e32 v155, v50, v50
	v_fmac_f32_e32 v156, v52, v52
	v_add_f32_e32 v155, v155, v156
	v_add_f32_e32 v154, v155, v154
	v_mov_b32_e32 v155, v154
	s_nop 1
	v_permlane16_swap_b32_e32 v155, v154
	s_waitcnt lgkmcnt(0)
	v_add_f32_e32 v154, v154, v155
	v_mov_b32_e32 v155, v154
	s_nop 1
	v_permlane32_swap_b32_e32 v154, v155
	s_and_saveexec_b64 s[0:1], vcc
	v_add_f32_e32 v154, v154, v155
	ds_write_b32 v186, v154 offset:2048
	s_or_b64 exec, exec, s[0:1]
	s_waitcnt vmcnt(5)
	v_cvt_f32_f16_sdwa v155, v150 dst_sel:DWORD dst_unused:UNUSED_PAD src0_sel:WORD_1
	v_cvt_f32_f16_e32 v154, v150
	v_cvt_f32_f16_sdwa v157, v151 dst_sel:DWORD dst_unused:UNUSED_PAD src0_sel:WORD_1
	v_cvt_f32_f16_e32 v156, v151
	v_cvt_f32_f16_sdwa v151, v152 dst_sel:DWORD dst_unused:UNUSED_PAD src0_sel:WORD_1
	v_cvt_f32_f16_e32 v150, v152
	v_pk_fma_f32 v[46:47], v[46:47], v[240:241], v[154:155]
	v_cvt_f32_f16_sdwa v155, v153 dst_sel:DWORD dst_unused:UNUSED_PAD src0_sel:WORD_1
	v_cvt_f32_f16_e32 v154, v153
	v_pk_fma_f32 v[42:43], v[42:43], v[232:233], v[150:151]
	s_waitcnt vmcnt(4)
	v_cvt_f32_f16_sdwa v151, v146 dst_sel:DWORD dst_unused:UNUSED_PAD src0_sel:WORD_1
	v_cvt_f32_f16_e32 v150, v146
	v_cvt_f32_f16_sdwa v153, v147 dst_sel:DWORD dst_unused:UNUSED_PAD src0_sel:WORD_1
	v_cvt_f32_f16_e32 v152, v147
	v_cvt_f32_f16_sdwa v147, v148 dst_sel:DWORD dst_unused:UNUSED_PAD src0_sel:WORD_1
	v_cvt_f32_f16_e32 v146, v148
	v_pk_fma_f32 v[48:49], v[48:49], v[238:239], v[156:157]
	v_pk_fma_f32 v[44:45], v[44:45], v[230:231], v[154:155]
	v_pk_fma_f32 v[38:39], v[38:39], v[236:237], v[150:151]
	v_pk_fma_f32 v[34:35], v[34:35], v[228:229], v[146:147]
	v_mul_f32_e32 v146, v47, v47
	v_mul_f32_e32 v147, v49, v49
	v_fmac_f32_e32 v146, v46, v46
	v_fmac_f32_e32 v147, v48, v48
	v_add_f32_e32 v146, v146, v147
	v_mul_f32_e32 v147, v43, v43
	v_mul_f32_e32 v148, v45, v45
	v_cvt_f32_f16_sdwa v151, v149 dst_sel:DWORD dst_unused:UNUSED_PAD src0_sel:WORD_1
	v_cvt_f32_f16_e32 v150, v149
	v_fmac_f32_e32 v147, v42, v42
	v_fmac_f32_e32 v148, v44, v44
	v_pk_fma_f32 v[40:41], v[40:41], v[234:235], v[152:153]
	v_add_f32_e32 v147, v147, v148
	v_add_f32_e32 v146, v146, v147
	v_mul_f32_e32 v147, v39, v39
	v_mul_f32_e32 v148, v41, v41
	v_fmac_f32_e32 v147, v38, v38
	v_fmac_f32_e32 v148, v40, v40
	v_pk_fma_f32 v[36:37], v[36:37], v[226:227], v[150:151]
	v_add_f32_e32 v147, v147, v148
	v_add_f32_e32 v146, v146, v147
	v_mul_f32_e32 v147, v35, v35
	v_mul_f32_e32 v148, v37, v37
	v_fmac_f32_e32 v147, v34, v34
	v_fmac_f32_e32 v148, v36, v36
	v_add_f32_e32 v147, v147, v148
	v_add_f32_e32 v146, v147, v146
	v_mov_b32_e32 v147, v146
	s_nop 1
	v_permlane16_swap_b32_e32 v147, v146
	s_waitcnt lgkmcnt(0)
	v_add_f32_e32 v146, v146, v147
	v_mov_b32_e32 v147, v146
	s_nop 1
	v_permlane32_swap_b32_e32 v146, v147
	s_and_saveexec_b64 s[0:1], vcc
	v_add_f32_e32 v146, v146, v147
	ds_write_b32 v186, v146 offset:2304
	s_or_b64 exec, exec, s[0:1]
	s_waitcnt vmcnt(3)
	v_cvt_f32_f16_sdwa v147, v138 dst_sel:DWORD dst_unused:UNUSED_PAD src0_sel:WORD_1
	v_cvt_f32_f16_e32 v146, v138
	v_cvt_f32_f16_sdwa v149, v139 dst_sel:DWORD dst_unused:UNUSED_PAD src0_sel:WORD_1
	v_cvt_f32_f16_e32 v148, v139
	v_cvt_f32_f16_sdwa v139, v140 dst_sel:DWORD dst_unused:UNUSED_PAD src0_sel:WORD_1
	v_cvt_f32_f16_e32 v138, v140
	v_pk_fma_f32 v[30:31], v[30:31], v[240:241], v[146:147]
	v_cvt_f32_f16_sdwa v147, v141 dst_sel:DWORD dst_unused:UNUSED_PAD src0_sel:WORD_1
	v_cvt_f32_f16_e32 v146, v141
	v_pk_fma_f32 v[26:27], v[26:27], v[232:233], v[138:139]
	s_waitcnt vmcnt(2)
	v_cvt_f32_f16_sdwa v139, v122 dst_sel:DWORD dst_unused:UNUSED_PAD src0_sel:WORD_1
	v_cvt_f32_f16_e32 v138, v122
	v_cvt_f32_f16_sdwa v141, v123 dst_sel:DWORD dst_unused:UNUSED_PAD src0_sel:WORD_1
	v_cvt_f32_f16_e32 v140, v123
	v_cvt_f32_f16_sdwa v123, v124 dst_sel:DWORD dst_unused:UNUSED_PAD src0_sel:WORD_1
	v_cvt_f32_f16_e32 v122, v124
	v_pk_fma_f32 v[32:33], v[32:33], v[238:239], v[148:149]
	v_pk_fma_f32 v[28:29], v[28:29], v[230:231], v[146:147]
	v_pk_fma_f32 v[22:23], v[22:23], v[236:237], v[138:139]
	v_pk_fma_f32 v[18:19], v[18:19], v[228:229], v[122:123]
	v_mul_f32_e32 v122, v31, v31
	v_mul_f32_e32 v123, v33, v33
	v_fmac_f32_e32 v122, v30, v30
	v_fmac_f32_e32 v123, v32, v32
	v_add_f32_e32 v122, v122, v123
	v_mul_f32_e32 v123, v27, v27
	v_mul_f32_e32 v124, v29, v29
	v_cvt_f32_f16_sdwa v139, v125 dst_sel:DWORD dst_unused:UNUSED_PAD src0_sel:WORD_1
	v_cvt_f32_f16_e32 v138, v125
	v_fmac_f32_e32 v123, v26, v26
	v_fmac_f32_e32 v124, v28, v28
	v_pk_fma_f32 v[24:25], v[24:25], v[234:235], v[140:141]
	v_add_f32_e32 v123, v123, v124
	v_add_f32_e32 v122, v122, v123
	v_mul_f32_e32 v123, v23, v23
	v_mul_f32_e32 v124, v25, v25
	v_fmac_f32_e32 v123, v22, v22
	v_fmac_f32_e32 v124, v24, v24
	v_pk_fma_f32 v[20:21], v[20:21], v[226:227], v[138:139]
	v_add_f32_e32 v123, v123, v124
	v_add_f32_e32 v122, v122, v123
	v_mul_f32_e32 v123, v19, v19
	v_mul_f32_e32 v124, v21, v21
	v_fmac_f32_e32 v123, v18, v18
	v_fmac_f32_e32 v124, v20, v20
	v_add_f32_e32 v123, v123, v124
	v_add_f32_e32 v122, v123, v122
	v_mov_b32_e32 v123, v122
	s_nop 1
	v_permlane16_swap_b32_e32 v123, v122
	s_waitcnt lgkmcnt(0)
	v_add_f32_e32 v122, v122, v123
	v_mov_b32_e32 v123, v122
	s_nop 1
	v_permlane32_swap_b32_e32 v122, v123
	s_and_saveexec_b64 s[0:1], vcc
	v_add_f32_e32 v122, v122, v123
	ds_write_b32 v186, v122 offset:2560
	s_or_b64 exec, exec, s[0:1]
	s_waitcnt vmcnt(1)
	v_cvt_f32_f16_sdwa v125, v142 dst_sel:DWORD dst_unused:UNUSED_PAD src0_sel:WORD_1
	v_cvt_f32_f16_e32 v124, v142
	v_cvt_f32_f16_sdwa v123, v143 dst_sel:DWORD dst_unused:UNUSED_PAD src0_sel:WORD_1
	v_cvt_f32_f16_e32 v122, v143
	v_pk_fma_f32 v[124:125], v[14:15], v[240:241], v[124:125]
	v_cvt_f32_f16_sdwa v15, v144 dst_sel:DWORD dst_unused:UNUSED_PAD src0_sel:WORD_1
	v_cvt_f32_f16_e32 v14, v144
	v_pk_fma_f32 v[122:123], v[16:17], v[238:239], v[122:123]
	v_cvt_f32_f16_sdwa v17, v145 dst_sel:DWORD dst_unused:UNUSED_PAD src0_sel:WORD_1
	v_cvt_f32_f16_e32 v16, v145
	v_pk_fma_f32 v[142:143], v[10:11], v[232:233], v[14:15]
	s_waitcnt vmcnt(0)
	v_cvt_f32_f16_sdwa v11, v126 dst_sel:DWORD dst_unused:UNUSED_PAD src0_sel:WORD_1
	v_cvt_f32_f16_e32 v10, v126
	v_pk_fma_f32 v[138:139], v[12:13], v[230:231], v[16:17]
	v_cvt_f32_f16_sdwa v13, v127 dst_sel:DWORD dst_unused:UNUSED_PAD src0_sel:WORD_1
	v_cvt_f32_f16_e32 v12, v127
	v_pk_fma_f32 v[140:141], v[6:7], v[236:237], v[10:11]
	v_cvt_f32_f16_sdwa v7, v128 dst_sel:DWORD dst_unused:UNUSED_PAD src0_sel:WORD_1
	v_cvt_f32_f16_e32 v6, v128
	v_pk_fma_f32 v[126:127], v[8:9], v[234:235], v[12:13]
	v_cvt_f32_f16_sdwa v9, v129 dst_sel:DWORD dst_unused:UNUSED_PAD src0_sel:WORD_1
	v_cvt_f32_f16_e32 v8, v129
	v_pk_fma_f32 v[144:145], v[2:3], v[228:229], v[6:7]
	v_mul_f32_e32 v2, v125, v125
	v_mul_f32_e32 v3, v123, v123
	v_fmac_f32_e32 v2, v124, v124
	v_fmac_f32_e32 v3, v122, v122
	v_pk_fma_f32 v[128:129], v[4:5], v[226:227], v[8:9]
	v_add_f32_e32 v2, v2, v3
	v_mul_f32_e32 v3, v143, v143
	v_mul_f32_e32 v4, v139, v139
	v_fmac_f32_e32 v3, v142, v142
	v_fmac_f32_e32 v4, v138, v138
	v_add_f32_e32 v3, v3, v4
	v_add_f32_e32 v2, v2, v3
	v_mul_f32_e32 v3, v141, v141
	v_mul_f32_e32 v4, v127, v127
	v_fmac_f32_e32 v3, v140, v140
	v_fmac_f32_e32 v4, v126, v126
	v_add_f32_e32 v3, v3, v4
	v_add_f32_e32 v2, v2, v3
	v_mul_f32_e32 v3, v145, v145
	v_mul_f32_e32 v4, v129, v129
	v_fmac_f32_e32 v3, v144, v144
	v_fmac_f32_e32 v4, v128, v128
	v_add_f32_e32 v3, v3, v4
	v_add_f32_e32 v2, v3, v2
	v_mov_b32_e32 v3, v2
	s_nop 1
	v_permlane16_swap_b32_e32 v3, v2
	s_waitcnt lgkmcnt(0)
	v_add_f32_e32 v2, v2, v3
	v_mov_b32_e32 v3, v2
	s_nop 1
	v_permlane32_swap_b32_e32 v2, v3
	s_and_saveexec_b64 s[0:1], vcc
	v_add_f32_e32 v2, v2, v3
	ds_write_b32 v186, v2 offset:2816
	s_or_b64 exec, exec, s[0:1]
	s_waitcnt lgkmcnt(0)
	s_barrier
	v_lshl_add_u32 v3, v254, 4, v250
	v_cmp_gt_i32_e64 s[6:7], 32, v3
	v_and_or_b32 v2, v3, 31, s65
	s_and_saveexec_b64 s[0:1], s[6:7]
	s_cbranch_execz .LBB0_476
	v_lshl_add_u32 v4, v2, 4, 0
	v_add_u32_e32 v4, 0x20400, v4
	ds_read_b128 v[4:7], v4
	s_ashr_i32 s53, s52, 31
	s_waitcnt lgkmcnt(0)
	v_mov_b32_e32 v9, v6
	v_add_u32_e32 v6, s83, v2
	v_mov_b32_e32 v8, v5
	v_mov_b32_e32 v5, v7
	v_ashrrev_i32_e32 v7, 31, v6
	v_pk_add_f32 v[4:5], v[8:9], v[4:5]
	v_lshl_add_u64 v[6:7], v[6:7], 4, s[8:9]
	v_pk_add_f32 v[4:5], v[4:5], v[4:5] op_sel:[0,1] op_sel_hi:[1,0]
	v_lshl_add_u64 v[6:7], s[52:53], 2, v[6:7]
	global_store_dword v[6:7], v4, off sc1

.LBB0_522:
	s_lshl_b32 s0, s38, 8
	v_mov_b32_e32 v243, v239
	v_mov_b32_e32 v250, v238
	s_or_b32 s0, s0, s55
	s_lshl_b32 s86, s83, 8
	v_lshl_add_u32 v216, v250, 3, s0
	s_ashr_i32 s0, s83, 5
	s_mul_hi_i32 s1, s0, 0x2400
	s_mulk_i32 s0, 0x2400
	s_lshl_b64 s[52:53], s[0:1], 2
	s_add_u32 s0, s20, s52
	s_addc_u32 s1, s21, s53
	v_ashrrev_i32_e32 v217, 31, v216
	v_lshl_add_u64 v[126:127], v[216:217], 2, s[0:1]
	global_load_dwordx2 v[228:229], v[126:127], off offset:16
	global_load_dwordx2 v[226:227], v[126:127], off offset:24
	global_load_dwordx2 v[236:237], v[126:127], off
	global_load_dwordx2 v[234:235], v[126:127], off offset:8
	global_load_dwordx2 v[220:221], v[126:127], off offset:528
	global_load_dwordx2 v[218:219], v[126:127], off offset:536
	global_load_dwordx2 v[232:233], v[126:127], off offset:512
	global_load_dwordx2 v[230:231], v[126:127], off offset:520
	s_mov_b32 s25, s24
	v_add_u32_e32 v249, s43, v243
	v_cmp_eq_u32_e32 vcc, 0, v250
	v_add_u32_e32 v114, s86, v249
	v_readlane_b32 s0, v255, 19
	v_readlane_b32 s1, v255, 20
	v_ashrrev_i32_e32 v115, 31, v114
	v_lshl_add_u64 v[116:117], v[216:217], 1, s[0:1]
	v_lshlrev_b64 v[214:215], 11, v[114:115]
	v_lshl_add_u64 v[114:115], v[116:117], 0, v[214:215]
	global_load_dwordx4 v[222:225], v[114:115], off
	global_load_dwordx4 v[186:189], v[114:115], off offset:256
	s_mov_b64 s[0:1], 0x8000
	v_lshl_add_u64 v[212:213], v[214:215], 0, s[0:1]
	s_mov_b64 s[0:1], 0x10000
	v_lshl_add_u64 v[114:115], v[116:117], 0, v[212:213]
	v_lshl_add_u64 v[210:211], v[214:215], 0, s[0:1]
	s_mov_b64 s[0:1], 0x18000
	global_load_dwordx4 v[182:185], v[114:115], off
	global_load_dwordx4 v[178:181], v[114:115], off offset:256
	v_lshl_add_u64 v[114:115], v[116:117], 0, v[210:211]
	v_lshl_add_u64 v[208:209], v[214:215], 0, s[0:1]
	global_load_dwordx4 v[174:177], v[114:115], off
	global_load_dwordx4 v[170:173], v[114:115], off offset:256
	v_lshl_add_u64 v[114:115], v[116:117], 0, v[208:209]
	v_lshl_add_u64 v[206:207], v[214:215], 0, s[58:59]
	s_mov_b64 s[0:1], 0x48000
	global_load_dwordx4 v[166:169], v[114:115], off
	global_load_dwordx4 v[162:165], v[114:115], off offset:256
	v_lshl_add_u64 v[114:115], v[116:117], 0, v[206:207]
	v_lshl_add_u64 v[204:205], v[214:215], 0, s[0:1]
	s_mov_b64 s[0:1], 0x50000
	global_load_dwordx4 v[158:161], v[114:115], off
	global_load_dwordx4 v[154:157], v[114:115], off offset:256
	v_lshl_add_u64 v[114:115], v[116:117], 0, v[204:205]
	v_lshl_add_u64 v[202:203], v[214:215], 0, s[0:1]
	s_mov_b64 s[0:1], 0x58000
	global_load_dwordx4 v[150:153], v[114:115], off
	global_load_dwordx4 v[146:149], v[114:115], off offset:256
	v_lshl_add_u64 v[114:115], v[116:117], 0, v[202:203]
	v_lshl_add_u64 v[200:201], v[214:215], 0, s[0:1]
	global_load_dwordx4 v[134:137], v[114:115], off
	global_load_dwordx4 v[126:129], v[114:115], off offset:256
	v_lshl_add_u64 v[114:115], v[116:117], 0, v[200:201]
	global_load_dwordx4 v[122:125], v[114:115], off
	s_nop 0
	global_load_dwordx4 v[114:117], v[114:115], off offset:256
	v_readlane_b32 s0, v255, 42
	v_readlane_b32 s1, v255, 43
	s_waitcnt vmcnt(16)
	v_pk_mul_f32 v[226:227], s[24:25], v[226:227]
	v_pk_mul_f32 v[234:235], v[234:235], s[24:25]
	v_pk_mul_f32 v[236:237], v[236:237], s[0:1]
	v_pk_mul_f32 v[228:229], s[0:1], v[228:229]
	v_pk_mul_f32 v[220:221], s[0:1], v[220:221]
	v_pk_mul_f32 v[232:233], s[0:1], v[232:233]
	v_pk_mul_f32 v[218:219], s[24:25], v[218:219]
	v_pk_mul_f32 v[230:231], s[24:25], v[230:231]
	s_waitcnt vmcnt(15)
	v_cvt_f32_f16_e32 v252, v222
	v_cvt_f32_f16_sdwa v253, v222 dst_sel:DWORD dst_unused:UNUSED_PAD src0_sel:WORD_1
	v_cvt_f32_f16_e32 v222, v223
	v_cvt_f32_f16_sdwa v223, v223 dst_sel:DWORD dst_unused:UNUSED_PAD src0_sel:WORD_1
	v_pk_fma_f32 v[142:143], v[142:143], v[236:237], v[252:253]
	v_pk_fma_f32 v[144:145], v[144:145], v[234:235], v[222:223]
	v_cvt_f32_f16_e32 v222, v224
	v_cvt_f32_f16_sdwa v223, v224 dst_sel:DWORD dst_unused:UNUSED_PAD src0_sel:WORD_1
	v_cvt_f32_f16_e32 v224, v225
	v_cvt_f32_f16_sdwa v225, v225 dst_sel:DWORD dst_unused:UNUSED_PAD src0_sel:WORD_1
	v_pk_fma_f32 v[138:139], v[138:139], v[228:229], v[222:223]
	s_waitcnt vmcnt(14)
	v_cvt_f32_f16_e32 v222, v186
	v_cvt_f32_f16_sdwa v223, v186 dst_sel:DWORD dst_unused:UNUSED_PAD src0_sel:WORD_1
	v_cvt_f32_f16_e32 v186, v187
	v_cvt_f32_f16_sdwa v187, v187 dst_sel:DWORD dst_unused:UNUSED_PAD src0_sel:WORD_1
	v_pk_fma_f32 v[140:141], v[140:141], v[226:227], v[224:225]
	v_pk_fma_f32 v[130:131], v[130:131], v[232:233], v[222:223]
	v_pk_fma_f32 v[132:133], v[132:133], v[230:231], v[186:187]
	v_cvt_f32_f16_e32 v186, v188
	v_cvt_f32_f16_sdwa v187, v188 dst_sel:DWORD dst_unused:UNUSED_PAD src0_sel:WORD_1
	v_cvt_f32_f16_e32 v188, v189
	v_cvt_f32_f16_sdwa v189, v189 dst_sel:DWORD dst_unused:UNUSED_PAD src0_sel:WORD_1
	v_pk_fma_f32 v[118:119], v[118:119], v[220:221], v[186:187]
	v_mul_f32_e32 v186, v143, v143
	v_mul_f32_e32 v187, v145, v145
	v_fmac_f32_e32 v186, v142, v142
	v_fmac_f32_e32 v187, v144, v144
	v_pk_fma_f32 v[120:121], v[120:121], v[218:219], v[188:189]
	v_add_f32_e32 v186, v186, v187
	v_mul_f32_e32 v187, v139, v139
	v_mul_f32_e32 v188, v141, v141
	v_fmac_f32_e32 v187, v138, v138
	v_fmac_f32_e32 v188, v140, v140
	v_add_f32_e32 v187, v187, v188
	v_add_f32_e32 v186, v186, v187
	v_mul_f32_e32 v187, v131, v131
	v_mul_f32_e32 v188, v133, v133
	v_fmac_f32_e32 v187, v130, v130
	v_fmac_f32_e32 v188, v132, v132
	v_add_f32_e32 v187, v187, v188
	v_add_f32_e32 v186, v186, v187
	v_mul_f32_e32 v187, v119, v119
	v_mul_f32_e32 v188, v121, v121
	v_fmac_f32_e32 v187, v118, v118
	v_fmac_f32_e32 v188, v120, v120
	v_add_f32_e32 v187, v187, v188
	v_add_f32_e32 v186, v187, v186
	v_mov_b32_e32 v187, v186
	s_nop 1
	v_permlane16_swap_b32_e32 v187, v186
	s_waitcnt lgkmcnt(0)
	v_add_f32_e32 v187, v186, v187
	v_mov_b32_e32 v188, v187
	s_nop 1
	v_permlane32_swap_b32_e32 v187, v188
	v_lshl_add_u32 v186, v243, 4, s78
	s_and_saveexec_b64 s[0:1], vcc
	v_add_f32_e32 v187, v187, v188
	ds_write_b32 v186, v187
	s_or_b64 exec, exec, s[0:1]
	s_waitcnt vmcnt(13)
	v_cvt_f32_f16_sdwa v189, v182 dst_sel:DWORD dst_unused:UNUSED_PAD src0_sel:WORD_1
	v_cvt_f32_f16_e32 v188, v182
	v_cvt_f32_f16_sdwa v223, v183 dst_sel:DWORD dst_unused:UNUSED_PAD src0_sel:WORD_1
	v_cvt_f32_f16_e32 v222, v183
	v_cvt_f32_f16_sdwa v183, v184 dst_sel:DWORD dst_unused:UNUSED_PAD src0_sel:WORD_1
	v_cvt_f32_f16_e32 v182, v184
	v_pk_fma_f32 v[110:111], v[110:111], v[236:237], v[188:189]
	v_cvt_f32_f16_sdwa v189, v185 dst_sel:DWORD dst_unused:UNUSED_PAD src0_sel:WORD_1
	v_cvt_f32_f16_e32 v188, v185
	v_pk_fma_f32 v[106:107], v[106:107], v[228:229], v[182:183]
	s_waitcnt vmcnt(12)
	v_cvt_f32_f16_sdwa v183, v178 dst_sel:DWORD dst_unused:UNUSED_PAD src0_sel:WORD_1
	v_cvt_f32_f16_e32 v182, v178
	v_cvt_f32_f16_sdwa v185, v179 dst_sel:DWORD dst_unused:UNUSED_PAD src0_sel:WORD_1
	v_cvt_f32_f16_e32 v184, v179
	v_cvt_f32_f16_sdwa v179, v180 dst_sel:DWORD dst_unused:UNUSED_PAD src0_sel:WORD_1
	v_cvt_f32_f16_e32 v178, v180
	v_pk_fma_f32 v[112:113], v[112:113], v[234:235], v[222:223]
	v_pk_fma_f32 v[108:109], v[108:109], v[226:227], v[188:189]
	v_pk_fma_f32 v[102:103], v[102:103], v[232:233], v[182:183]
	v_pk_fma_f32 v[98:99], v[98:99], v[220:221], v[178:179]
	v_mul_f32_e32 v178, v111, v111
	v_mul_f32_e32 v179, v113, v113
	v_fmac_f32_e32 v178, v110, v110
	v_fmac_f32_e32 v179, v112, v112
	v_add_f32_e32 v178, v178, v179
	v_mul_f32_e32 v179, v107, v107
	v_mul_f32_e32 v180, v109, v109
	v_cvt_f32_f16_sdwa v183, v181 dst_sel:DWORD dst_unused:UNUSED_PAD src0_sel:WORD_1
	v_cvt_f32_f16_e32 v182, v181
	v_fmac_f32_e32 v179, v106, v106
	v_fmac_f32_e32 v180, v108, v108
	v_pk_fma_f32 v[104:105], v[104:105], v[230:231], v[184:185]
	v_add_f32_e32 v179, v179, v180
	v_add_f32_e32 v178, v178, v179
	v_mul_f32_e32 v179, v103, v103
	v_mul_f32_e32 v180, v105, v105
	v_fmac_f32_e32 v179, v102, v102
	v_fmac_f32_e32 v180, v104, v104
	v_pk_fma_f32 v[100:101], v[100:101], v[218:219], v[182:183]
	v_add_f32_e32 v179, v179, v180
	v_add_f32_e32 v178, v178, v179
	v_mul_f32_e32 v179, v99, v99
	v_mul_f32_e32 v180, v101, v101
	v_fmac_f32_e32 v179, v98, v98
	v_fmac_f32_e32 v180, v100, v100
	v_add_f32_e32 v179, v179, v180
	v_add_f32_e32 v178, v179, v178
	v_mov_b32_e32 v179, v178
	s_nop 1
	v_permlane16_swap_b32_e32 v179, v178
	s_waitcnt lgkmcnt(0)
	v_add_f32_e32 v178, v178, v179
	v_mov_b32_e32 v179, v178
	s_nop 1
	v_permlane32_swap_b32_e32 v178, v179
	s_and_saveexec_b64 s[0:1], vcc
	v_add_f32_e32 v178, v178, v179
	ds_write_b32 v186, v178 offset:256
	s_or_b64 exec, exec, s[0:1]
	s_waitcnt vmcnt(11)
	v_cvt_f32_f16_sdwa v179, v174 dst_sel:DWORD dst_unused:UNUSED_PAD src0_sel:WORD_1
	v_cvt_f32_f16_e32 v178, v174
	v_cvt_f32_f16_sdwa v181, v175 dst_sel:DWORD dst_unused:UNUSED_PAD src0_sel:WORD_1
	v_cvt_f32_f16_e32 v180, v175
	v_cvt_f32_f16_sdwa v175, v176 dst_sel:DWORD dst_unused:UNUSED_PAD src0_sel:WORD_1
	v_cvt_f32_f16_e32 v174, v176
	v_pk_fma_f32 v[94:95], v[94:95], v[236:237], v[178:179]
	v_cvt_f32_f16_sdwa v179, v177 dst_sel:DWORD dst_unused:UNUSED_PAD src0_sel:WORD_1
	v_cvt_f32_f16_e32 v178, v177
	v_pk_fma_f32 v[90:91], v[90:91], v[228:229], v[174:175]
	s_waitcnt vmcnt(10)
	v_cvt_f32_f16_sdwa v175, v170 dst_sel:DWORD dst_unused:UNUSED_PAD src0_sel:WORD_1
	v_cvt_f32_f16_e32 v174, v170
	v_cvt_f32_f16_sdwa v177, v171 dst_sel:DWORD dst_unused:UNUSED_PAD src0_sel:WORD_1
	v_cvt_f32_f16_e32 v176, v171
	v_cvt_f32_f16_sdwa v171, v172 dst_sel:DWORD dst_unused:UNUSED_PAD src0_sel:WORD_1
	v_cvt_f32_f16_e32 v170, v172
	v_pk_fma_f32 v[96:97], v[96:97], v[234:235], v[180:181]
	v_pk_fma_f32 v[92:93], v[92:93], v[226:227], v[178:179]
	v_pk_fma_f32 v[86:87], v[86:87], v[232:233], v[174:175]
	v_pk_fma_f32 v[82:83], v[82:83], v[220:221], v[170:171]
	v_mul_f32_e32 v170, v95, v95
	v_mul_f32_e32 v171, v97, v97
	v_fmac_f32_e32 v170, v94, v94
	v_fmac_f32_e32 v171, v96, v96
	v_add_f32_e32 v170, v170, v171
	v_mul_f32_e32 v171, v91, v91
	v_mul_f32_e32 v172, v93, v93
	v_cvt_f32_f16_sdwa v175, v173 dst_sel:DWORD dst_unused:UNUSED_PAD src0_sel:WORD_1
	v_cvt_f32_f16_e32 v174, v173
	v_fmac_f32_e32 v171, v90, v90
	v_fmac_f32_e32 v172, v92, v92
	v_pk_fma_f32 v[88:89], v[88:89], v[230:231], v[176:177]
	v_add_f32_e32 v171, v171, v172
	v_add_f32_e32 v170, v170, v171
	v_mul_f32_e32 v171, v87, v87
	v_mul_f32_e32 v172, v89, v89
	v_fmac_f32_e32 v171, v86, v86
	v_fmac_f32_e32 v172, v88, v88
	v_pk_fma_f32 v[84:85], v[84:85], v[218:219], v[174:175]
	v_add_f32_e32 v171, v171, v172
	v_add_f32_e32 v170, v170, v171
	v_mul_f32_e32 v171, v83, v83
	v_mul_f32_e32 v172, v85, v85
	v_fmac_f32_e32 v171, v82, v82
	v_fmac_f32_e32 v172, v84, v84
	v_add_f32_e32 v171, v171, v172
	v_add_f32_e32 v170, v171, v170
	v_mov_b32_e32 v171, v170
	s_nop 1
	v_permlane16_swap_b32_e32 v171, v170
	s_waitcnt lgkmcnt(0)
	v_add_f32_e32 v170, v170, v171
	v_mov_b32_e32 v171, v170
	s_nop 1
	v_permlane32_swap_b32_e32 v170, v171
	s_mov_b64 s[0:1], exec
	s_and_b64 s[2:3], s[0:1], vcc
	v_mov_b32_e32 v252, v242
	s_mov_b64 exec, s[2:3]
	v_add_f32_e32 v170, v170, v171
	ds_write_b32 v186, v170 offset:512
	s_or_b64 exec, exec, s[0:1]
	s_waitcnt vmcnt(9)
	v_cvt_f32_f16_sdwa v171, v166 dst_sel:DWORD dst_unused:UNUSED_PAD src0_sel:WORD_1
	v_cvt_f32_f16_e32 v170, v166
	v_cvt_f32_f16_sdwa v173, v167 dst_sel:DWORD dst_unused:UNUSED_PAD src0_sel:WORD_1
	v_cvt_f32_f16_e32 v172, v167
	v_cvt_f32_f16_sdwa v167, v168 dst_sel:DWORD dst_unused:UNUSED_PAD src0_sel:WORD_1
	v_cvt_f32_f16_e32 v166, v168
	v_pk_fma_f32 v[78:79], v[78:79], v[236:237], v[170:171]
	v_cvt_f32_f16_sdwa v171, v169 dst_sel:DWORD dst_unused:UNUSED_PAD src0_sel:WORD_1
	v_cvt_f32_f16_e32 v170, v169
	v_pk_fma_f32 v[74:75], v[74:75], v[228:229], v[166:167]
	s_waitcnt vmcnt(8)
	v_cvt_f32_f16_sdwa v167, v162 dst_sel:DWORD dst_unused:UNUSED_PAD src0_sel:WORD_1
	v_cvt_f32_f16_e32 v166, v162
	v_cvt_f32_f16_sdwa v169, v163 dst_sel:DWORD dst_unused:UNUSED_PAD src0_sel:WORD_1
	v_cvt_f32_f16_e32 v168, v163
	v_cvt_f32_f16_sdwa v163, v164 dst_sel:DWORD dst_unused:UNUSED_PAD src0_sel:WORD_1
	v_cvt_f32_f16_e32 v162, v164
	v_pk_fma_f32 v[80:81], v[80:81], v[234:235], v[172:173]
	v_pk_fma_f32 v[76:77], v[76:77], v[226:227], v[170:171]
	v_pk_fma_f32 v[70:71], v[70:71], v[232:233], v[166:167]
	v_pk_fma_f32 v[66:67], v[66:67], v[220:221], v[162:163]
	v_mul_f32_e32 v162, v79, v79
	v_mul_f32_e32 v163, v81, v81
	v_fmac_f32_e32 v162, v78, v78
	v_fmac_f32_e32 v163, v80, v80
	v_add_f32_e32 v162, v162, v163
	v_mul_f32_e32 v163, v75, v75
	v_mul_f32_e32 v164, v77, v77
	v_cvt_f32_f16_sdwa v167, v165 dst_sel:DWORD dst_unused:UNUSED_PAD src0_sel:WORD_1
	v_cvt_f32_f16_e32 v166, v165
	v_fmac_f32_e32 v163, v74, v74
	v_fmac_f32_e32 v164, v76, v76
	v_pk_fma_f32 v[72:73], v[72:73], v[230:231], v[168:169]
	v_add_f32_e32 v163, v163, v164
	v_add_f32_e32 v162, v162, v163
	v_mul_f32_e32 v163, v71, v71
	v_mul_f32_e32 v164, v73, v73
	v_fmac_f32_e32 v163, v70, v70
	v_fmac_f32_e32 v164, v72, v72
	v_pk_fma_f32 v[68:69], v[68:69], v[218:219], v[166:167]
	v_add_f32_e32 v163, v163, v164
	v_add_f32_e32 v162, v162, v163
	v_mul_f32_e32 v163, v67, v67
	v_mul_f32_e32 v164, v69, v69
	v_fmac_f32_e32 v163, v66, v66
	v_fmac_f32_e32 v164, v68, v68
	v_add_f32_e32 v163, v163, v164
	v_add_f32_e32 v162, v163, v162
	v_mov_b32_e32 v163, v162
	s_nop 1
	v_permlane16_swap_b32_e32 v163, v162
	s_waitcnt lgkmcnt(0)
	v_add_f32_e32 v162, v162, v163
	v_mov_b32_e32 v163, v162
	s_nop 1
	v_permlane32_swap_b32_e32 v162, v163
	s_and_saveexec_b64 s[0:1], vcc
	v_add_f32_e32 v162, v162, v163
	ds_write_b32 v186, v162 offset:768
	s_or_b64 exec, exec, s[0:1]
	s_waitcnt vmcnt(7)
	v_cvt_f32_f16_sdwa v163, v158 dst_sel:DWORD dst_unused:UNUSED_PAD src0_sel:WORD_1
	v_cvt_f32_f16_e32 v162, v158
	v_cvt_f32_f16_sdwa v165, v159 dst_sel:DWORD dst_unused:UNUSED_PAD src0_sel:WORD_1
	v_cvt_f32_f16_e32 v164, v159
	v_cvt_f32_f16_sdwa v159, v160 dst_sel:DWORD dst_unused:UNUSED_PAD src0_sel:WORD_1
	v_cvt_f32_f16_e32 v158, v160
	v_pk_fma_f32 v[62:63], v[62:63], v[236:237], v[162:163]
	v_cvt_f32_f16_sdwa v163, v161 dst_sel:DWORD dst_unused:UNUSED_PAD src0_sel:WORD_1
	v_cvt_f32_f16_e32 v162, v161
	v_pk_fma_f32 v[58:59], v[58:59], v[228:229], v[158:159]
	s_waitcnt vmcnt(6)
	v_cvt_f32_f16_sdwa v159, v154 dst_sel:DWORD dst_unused:UNUSED_PAD src0_sel:WORD_1
	v_cvt_f32_f16_e32 v158, v154
	v_cvt_f32_f16_sdwa v161, v155 dst_sel:DWORD dst_unused:UNUSED_PAD src0_sel:WORD_1
	v_cvt_f32_f16_e32 v160, v155
	v_cvt_f32_f16_sdwa v155, v156 dst_sel:DWORD dst_unused:UNUSED_PAD src0_sel:WORD_1
	v_cvt_f32_f16_e32 v154, v156
	v_pk_fma_f32 v[64:65], v[64:65], v[234:235], v[164:165]
	v_pk_fma_f32 v[60:61], v[60:61], v[226:227], v[162:163]
	v_pk_fma_f32 v[54:55], v[54:55], v[232:233], v[158:159]
	v_pk_fma_f32 v[50:51], v[50:51], v[220:221], v[154:155]
	v_mul_f32_e32 v154, v63, v63
	v_mul_f32_e32 v155, v65, v65
	v_fmac_f32_e32 v154, v62, v62
	v_fmac_f32_e32 v155, v64, v64
	v_add_f32_e32 v154, v154, v155
	v_mul_f32_e32 v155, v59, v59
	v_mul_f32_e32 v156, v61, v61
	v_cvt_f32_f16_sdwa v159, v157 dst_sel:DWORD dst_unused:UNUSED_PAD src0_sel:WORD_1
	v_cvt_f32_f16_e32 v158, v157
	v_fmac_f32_e32 v155, v58, v58
	v_fmac_f32_e32 v156, v60, v60
	v_pk_fma_f32 v[56:57], v[56:57], v[230:231], v[160:161]
	v_add_f32_e32 v155, v155, v156
	v_add_f32_e32 v154, v154, v155
	v_mul_f32_e32 v155, v55, v55
	v_mul_f32_e32 v156, v57, v57
	v_fmac_f32_e32 v155, v54, v54
	v_fmac_f32_e32 v156, v56, v56
	v_pk_fma_f32 v[52:53], v[52:53], v[218:219], v[158:159]
	v_add_f32_e32 v155, v155, v156
	v_add_f32_e32 v154, v154, v155
	v_mul_f32_e32 v155, v51, v51
	v_mul_f32_e32 v156, v53, v53
	v_fmac_f32_e32 v155, v50, v50
	v_fmac_f32_e32 v156, v52, v52
	v_add_f32_e32 v155, v155, v156
	v_add_f32_e32 v154, v155, v154
	v_mov_b32_e32 v155, v154
	s_nop 1
	v_permlane16_swap_b32_e32 v155, v154
	s_waitcnt lgkmcnt(0)
	v_add_f32_e32 v154, v154, v155
	v_mov_b32_e32 v155, v154
	s_nop 1
	v_permlane32_swap_b32_e32 v154, v155
	s_and_saveexec_b64 s[0:1], vcc
	v_add_f32_e32 v154, v154, v155
	ds_write_b32 v186, v154 offset:2048
	s_or_b64 exec, exec, s[0:1]
	s_waitcnt vmcnt(5)
	v_cvt_f32_f16_sdwa v155, v150 dst_sel:DWORD dst_unused:UNUSED_PAD src0_sel:WORD_1
	v_cvt_f32_f16_e32 v154, v150
	v_cvt_f32_f16_sdwa v157, v151 dst_sel:DWORD dst_unused:UNUSED_PAD src0_sel:WORD_1
	v_cvt_f32_f16_e32 v156, v151
	v_cvt_f32_f16_sdwa v151, v152 dst_sel:DWORD dst_unused:UNUSED_PAD src0_sel:WORD_1
	v_cvt_f32_f16_e32 v150, v152
	v_pk_fma_f32 v[46:47], v[46:47], v[236:237], v[154:155]
	v_cvt_f32_f16_sdwa v155, v153 dst_sel:DWORD dst_unused:UNUSED_PAD src0_sel:WORD_1
	v_cvt_f32_f16_e32 v154, v153
	v_pk_fma_f32 v[42:43], v[42:43], v[228:229], v[150:151]
	s_waitcnt vmcnt(4)
	v_cvt_f32_f16_sdwa v151, v146 dst_sel:DWORD dst_unused:UNUSED_PAD src0_sel:WORD_1
	v_cvt_f32_f16_e32 v150, v146
	v_cvt_f32_f16_sdwa v153, v147 dst_sel:DWORD dst_unused:UNUSED_PAD src0_sel:WORD_1
	v_cvt_f32_f16_e32 v152, v147
	v_cvt_f32_f16_sdwa v147, v148 dst_sel:DWORD dst_unused:UNUSED_PAD src0_sel:WORD_1
	v_cvt_f32_f16_e32 v146, v148
	v_pk_fma_f32 v[48:49], v[48:49], v[234:235], v[156:157]
	v_pk_fma_f32 v[44:45], v[44:45], v[226:227], v[154:155]
	v_pk_fma_f32 v[38:39], v[38:39], v[232:233], v[150:151]
	v_pk_fma_f32 v[34:35], v[34:35], v[220:221], v[146:147]
	v_mul_f32_e32 v146, v47, v47
	v_mul_f32_e32 v147, v49, v49
	v_fmac_f32_e32 v146, v46, v46
	v_fmac_f32_e32 v147, v48, v48
	v_add_f32_e32 v146, v146, v147
	v_mul_f32_e32 v147, v43, v43
	v_mul_f32_e32 v148, v45, v45
	v_cvt_f32_f16_sdwa v151, v149 dst_sel:DWORD dst_unused:UNUSED_PAD src0_sel:WORD_1
	v_cvt_f32_f16_e32 v150, v149
	v_fmac_f32_e32 v147, v42, v42
	v_fmac_f32_e32 v148, v44, v44
	v_pk_fma_f32 v[40:41], v[40:41], v[230:231], v[152:153]
	v_add_f32_e32 v147, v147, v148
	v_add_f32_e32 v146, v146, v147
	v_mul_f32_e32 v147, v39, v39
	v_mul_f32_e32 v148, v41, v41
	v_fmac_f32_e32 v147, v38, v38
	v_fmac_f32_e32 v148, v40, v40
	v_pk_fma_f32 v[36:37], v[36:37], v[218:219], v[150:151]
	v_add_f32_e32 v147, v147, v148
	v_add_f32_e32 v146, v146, v147
	v_mul_f32_e32 v147, v35, v35
	v_mul_f32_e32 v148, v37, v37
	v_fmac_f32_e32 v147, v34, v34
	v_fmac_f32_e32 v148, v36, v36
	v_add_f32_e32 v147, v147, v148
	v_add_f32_e32 v146, v147, v146
	v_mov_b32_e32 v147, v146
	s_nop 1
	v_permlane16_swap_b32_e32 v147, v146
	s_waitcnt lgkmcnt(0)
	v_add_f32_e32 v146, v146, v147
	v_mov_b32_e32 v147, v146
	s_nop 1
	v_permlane32_swap_b32_e32 v146, v147
	s_and_saveexec_b64 s[0:1], vcc
	v_add_f32_e32 v146, v146, v147
	ds_write_b32 v186, v146 offset:2304
	s_or_b64 exec, exec, s[0:1]
	s_waitcnt vmcnt(3)
	v_cvt_f32_f16_sdwa v147, v134 dst_sel:DWORD dst_unused:UNUSED_PAD src0_sel:WORD_1
	v_cvt_f32_f16_e32 v146, v134
	v_cvt_f32_f16_sdwa v149, v135 dst_sel:DWORD dst_unused:UNUSED_PAD src0_sel:WORD_1
	v_cvt_f32_f16_e32 v148, v135
	v_cvt_f32_f16_sdwa v135, v136 dst_sel:DWORD dst_unused:UNUSED_PAD src0_sel:WORD_1
	v_cvt_f32_f16_e32 v134, v136
	v_pk_fma_f32 v[30:31], v[30:31], v[236:237], v[146:147]
	v_cvt_f32_f16_sdwa v147, v137 dst_sel:DWORD dst_unused:UNUSED_PAD src0_sel:WORD_1
	v_cvt_f32_f16_e32 v146, v137
	v_pk_fma_f32 v[26:27], v[26:27], v[228:229], v[134:135]
	s_waitcnt vmcnt(2)
	v_cvt_f32_f16_sdwa v135, v126 dst_sel:DWORD dst_unused:UNUSED_PAD src0_sel:WORD_1
	v_cvt_f32_f16_e32 v134, v126
	v_cvt_f32_f16_sdwa v137, v127 dst_sel:DWORD dst_unused:UNUSED_PAD src0_sel:WORD_1
	v_cvt_f32_f16_e32 v136, v127
	v_cvt_f32_f16_sdwa v127, v128 dst_sel:DWORD dst_unused:UNUSED_PAD src0_sel:WORD_1
	v_cvt_f32_f16_e32 v126, v128
	v_pk_fma_f32 v[32:33], v[32:33], v[234:235], v[148:149]
	v_pk_fma_f32 v[28:29], v[28:29], v[226:227], v[146:147]
	v_pk_fma_f32 v[22:23], v[22:23], v[232:233], v[134:135]
	v_pk_fma_f32 v[18:19], v[18:19], v[220:221], v[126:127]
	v_mul_f32_e32 v126, v31, v31
	v_mul_f32_e32 v127, v33, v33
	v_fmac_f32_e32 v126, v30, v30
	v_fmac_f32_e32 v127, v32, v32
	v_add_f32_e32 v126, v126, v127
	v_mul_f32_e32 v127, v27, v27
	v_mul_f32_e32 v128, v29, v29
	v_cvt_f32_f16_sdwa v135, v129 dst_sel:DWORD dst_unused:UNUSED_PAD src0_sel:WORD_1
	v_cvt_f32_f16_e32 v134, v129
	v_fmac_f32_e32 v127, v26, v26
	v_fmac_f32_e32 v128, v28, v28
	v_pk_fma_f32 v[24:25], v[24:25], v[230:231], v[136:137]
	v_add_f32_e32 v127, v127, v128
	v_add_f32_e32 v126, v126, v127
	v_mul_f32_e32 v127, v23, v23
	v_mul_f32_e32 v128, v25, v25
	v_fmac_f32_e32 v127, v22, v22
	v_fmac_f32_e32 v128, v24, v24
	v_pk_fma_f32 v[20:21], v[20:21], v[218:219], v[134:135]
	v_add_f32_e32 v127, v127, v128
	v_add_f32_e32 v126, v126, v127
	v_mul_f32_e32 v127, v19, v19
	v_mul_f32_e32 v128, v21, v21
	v_fmac_f32_e32 v127, v18, v18
	v_fmac_f32_e32 v128, v20, v20
	v_add_f32_e32 v127, v127, v128
	v_add_f32_e32 v126, v127, v126
	v_mov_b32_e32 v127, v126
	s_nop 1
	v_permlane16_swap_b32_e32 v127, v126
	s_waitcnt lgkmcnt(0)
	v_add_f32_e32 v126, v126, v127
	v_mov_b32_e32 v127, v126
	s_nop 1
	v_permlane32_swap_b32_e32 v126, v127
	s_and_saveexec_b64 s[0:1], vcc
	v_add_f32_e32 v126, v126, v127
	ds_write_b32 v186, v126 offset:2560
	s_or_b64 exec, exec, s[0:1]
	s_waitcnt vmcnt(1)
	v_cvt_f32_f16_sdwa v127, v122 dst_sel:DWORD dst_unused:UNUSED_PAD src0_sel:WORD_1
	v_cvt_f32_f16_e32 v126, v122
	v_cvt_f32_f16_sdwa v129, v123 dst_sel:DWORD dst_unused:UNUSED_PAD src0_sel:WORD_1
	v_cvt_f32_f16_e32 v128, v123
	v_pk_fma_f32 v[126:127], v[14:15], v[236:237], v[126:127]
	v_cvt_f32_f16_sdwa v15, v124 dst_sel:DWORD dst_unused:UNUSED_PAD src0_sel:WORD_1
	v_cvt_f32_f16_e32 v14, v124
	v_pk_fma_f32 v[122:123], v[16:17], v[234:235], v[128:129]
	v_cvt_f32_f16_sdwa v17, v125 dst_sel:DWORD dst_unused:UNUSED_PAD src0_sel:WORD_1
	v_cvt_f32_f16_e32 v16, v125
	v_pk_fma_f32 v[134:135], v[10:11], v[228:229], v[14:15]
	s_waitcnt vmcnt(0)
	v_cvt_f32_f16_sdwa v11, v114 dst_sel:DWORD dst_unused:UNUSED_PAD src0_sel:WORD_1
	v_cvt_f32_f16_e32 v10, v114
	v_pk_fma_f32 v[128:129], v[12:13], v[226:227], v[16:17]
	v_cvt_f32_f16_sdwa v13, v115 dst_sel:DWORD dst_unused:UNUSED_PAD src0_sel:WORD_1
	v_cvt_f32_f16_e32 v12, v115
	v_pk_fma_f32 v[124:125], v[6:7], v[232:233], v[10:11]
	v_cvt_f32_f16_sdwa v7, v116 dst_sel:DWORD dst_unused:UNUSED_PAD src0_sel:WORD_1
	v_cvt_f32_f16_e32 v6, v116
	v_pk_fma_f32 v[114:115], v[8:9], v[230:231], v[12:13]
	v_cvt_f32_f16_sdwa v9, v117 dst_sel:DWORD dst_unused:UNUSED_PAD src0_sel:WORD_1
	v_cvt_f32_f16_e32 v8, v117
	v_pk_fma_f32 v[136:137], v[2:3], v[220:221], v[6:7]
	v_mul_f32_e32 v2, v127, v127
	v_mul_f32_e32 v3, v123, v123
	v_fmac_f32_e32 v2, v126, v126
	v_fmac_f32_e32 v3, v122, v122
	v_pk_fma_f32 v[116:117], v[4:5], v[218:219], v[8:9]
	v_add_f32_e32 v2, v2, v3
	v_mul_f32_e32 v3, v135, v135
	v_mul_f32_e32 v4, v129, v129
	v_fmac_f32_e32 v3, v134, v134
	v_fmac_f32_e32 v4, v128, v128
	v_add_f32_e32 v3, v3, v4
	v_add_f32_e32 v2, v2, v3
	v_mul_f32_e32 v3, v125, v125
	v_mul_f32_e32 v4, v115, v115
	v_fmac_f32_e32 v3, v124, v124
	v_fmac_f32_e32 v4, v114, v114
	v_add_f32_e32 v3, v3, v4
	v_add_f32_e32 v2, v2, v3
	v_mul_f32_e32 v3, v137, v137
	v_mul_f32_e32 v4, v117, v117
	v_fmac_f32_e32 v3, v136, v136
	v_fmac_f32_e32 v4, v116, v116
	v_add_f32_e32 v3, v3, v4
	v_add_f32_e32 v2, v3, v2
	v_mov_b32_e32 v3, v2
	s_nop 1
	v_permlane16_swap_b32_e32 v3, v2
	s_waitcnt lgkmcnt(0)
	v_add_f32_e32 v2, v2, v3
	v_mov_b32_e32 v3, v2
	s_nop 1
	v_permlane32_swap_b32_e32 v2, v3
	s_and_saveexec_b64 s[0:1], vcc
	v_add_f32_e32 v2, v2, v3
	ds_write_b32 v186, v2 offset:2816
	s_or_b64 exec, exec, s[0:1]
	s_waitcnt lgkmcnt(0)
	s_barrier
	v_lshl_add_u32 v3, v250, 4, v243
	v_cmp_gt_i32_e64 s[6:7], 32, v3
	v_and_or_b32 v2, v3, 31, s69
	s_and_saveexec_b64 s[0:1], s[6:7]
	s_cbranch_execz .LBB0_540
	v_lshl_add_u32 v4, v2, 4, 0
	v_add_u32_e32 v4, 0x20400, v4
	ds_read_b128 v[4:7], v4
	s_ashr_i32 s39, s38, 31
	s_waitcnt lgkmcnt(0)
	v_mov_b32_e32 v9, v6
	v_add_u32_e32 v6, s86, v2
	v_mov_b32_e32 v8, v5
	v_mov_b32_e32 v5, v7
	v_ashrrev_i32_e32 v7, 31, v6
	v_pk_add_f32 v[4:5], v[8:9], v[4:5]
	v_lshl_add_u64 v[6:7], v[6:7], 4, s[8:9]
	v_pk_add_f32 v[4:5], v[4:5], v[4:5] op_sel:[0,1] op_sel_hi:[1,0]
	v_lshl_add_u64 v[6:7], s[38:39], 2, v[6:7]
	global_store_dword v[6:7], v4, off sc1

.LBB0_595:
	s_lshl_b32 s0, s52, 8
	v_mov_b32_e32 v193, v189
	v_mov_b32_e32 v194, v188
	s_or_b32 s0, s0, s55
	s_lshl_b32 s2, s14, 8
	v_lshl_add_u32 v166, v194, 3, s0
	s_ashr_i32 s0, s14, 5
	s_mul_hi_i32 s1, s0, 0x2400
	s_mulk_i32 s0, 0x2400
	s_lshl_b64 s[64:65], s[0:1], 2
	s_add_u32 s0, s20, s64
	v_ashrrev_i32_e32 v167, 31, v166
	s_addc_u32 s1, s21, s65
	v_lshlrev_b64 v[156:157], 2, v[166:167]
	v_lshl_add_u64 v[138:139], s[0:1], 0, v[156:157]
	global_load_dwordx2 v[170:171], v[138:139], off offset:16
	global_load_dwordx2 v[168:169], v[138:139], off offset:24
	global_load_dwordx2 v[178:179], v[138:139], off
	global_load_dwordx2 v[176:177], v[138:139], off offset:8
	global_load_dwordx2 v[174:175], v[138:139], off offset:528
	global_load_dwordx2 v[172:173], v[138:139], off offset:536
	global_load_dwordx2 v[182:183], v[138:139], off offset:512
	global_load_dwordx2 v[180:181], v[138:139], off offset:520
	s_mov_b32 s25, s24
	v_add_u32_e32 v192, s43, v193
	v_add_u32_e32 v186, s2, v192
	v_ashrrev_i32_e32 v187, 31, v186
	v_add_u32_e32 v208, 16, v186
	v_ashrrev_i32_e32 v209, 31, v208
	v_lshlrev_b64 v[158:159], 11, v[186:187]
	v_cmp_eq_u32_e32 vcc, 0, v194
	v_readlane_b32 s0, v255, 19
	v_readlane_b32 s1, v255, 20
	v_lshlrev_b64 v[130:131], 12, v[186:187]
	v_lshl_add_u64 v[184:185], s[0:1], 0, v[156:157]
	v_lshl_add_u64 v[130:131], v[184:185], 0, v[130:131]
	global_load_dwordx4 v[162:165], v[130:131], off offset:16
	global_load_dwordx4 v[196:199], v[130:131], off
	global_load_dwordx4 v[200:203], v[130:131], off offset:528
	global_load_dwordx4 v[204:207], v[130:131], off offset:512
	v_lshlrev_b64 v[130:131], 12, v[208:209]
	v_lshl_add_u64 v[134:135], v[184:185], 0, v[130:131]
	global_load_dwordx4 v[138:141], v[134:135], off offset:16
	global_load_dwordx4 v[142:145], v[134:135], off
	global_load_dwordx4 v[130:133], v[134:135], off offset:528
	s_nop 0
	global_load_dwordx4 v[134:137], v[134:135], off offset:512
	v_readlane_b32 s0, v255, 42
	v_readlane_b32 s1, v255, 43
	s_waitcnt vmcnt(8)
	v_pk_mul_f32 v[168:169], s[24:25], v[168:169]
	v_pk_mul_f32 v[176:177], v[176:177], s[24:25]
	v_pk_mul_f32 v[178:179], v[178:179], s[0:1]
	v_pk_mul_f32 v[170:171], s[0:1], v[170:171]
	v_pk_mul_f32 v[174:175], s[0:1], v[174:175]
	v_pk_mul_f32 v[182:183], s[0:1], v[182:183]
	v_pk_mul_f32 v[180:181], s[24:25], v[180:181]
	v_pk_mul_f32 v[172:173], s[24:25], v[172:173]
	s_waitcnt vmcnt(7)
	v_pk_fma_f32 v[124:125], v[124:125], v[168:169], v[164:165]
	s_waitcnt vmcnt(6)
	v_pk_fma_f32 v[160:161], v[126:127], v[178:179], v[196:197]
	v_pk_fma_f32 v[128:129], v[128:129], v[176:177], v[198:199]
	v_pk_fma_f32 v[126:127], v[122:123], v[170:171], v[162:163]
	v_med3_f32 v122, v160, s95, v247
	v_med3_f32 v123, v161, s95, v247
	v_cvt_pk_f16_f32 v162, v122, v123
	v_med3_f32 v122, v128, s95, v247
	v_med3_f32 v123, v129, s95, v247
	v_cvt_pk_f16_f32 v163, v122, v123
	v_med3_f32 v122, v126, s95, v247
	v_med3_f32 v123, v127, s95, v247
	v_cvt_pk_f16_f32 v164, v122, v123
	v_med3_f32 v122, v124, s95, v247
	v_med3_f32 v123, v125, s95, v247
	v_cvt_pk_f16_f32 v165, v122, v123
	v_lshl_add_u64 v[196:197], s[26:27], 0, v[158:159]
	v_lshlrev_b64 v[122:123], 1, v[166:167]
	v_lshl_add_u64 v[166:167], v[196:197], 0, v[122:123]
	s_waitcnt vmcnt(4)
	v_pk_fma_f32 v[118:119], v[118:119], v[182:183], v[204:205]
	global_store_dwordx4 v[166:167], v[162:165], off
	v_pk_fma_f32 v[120:121], v[120:121], v[180:181], v[206:207]
	v_pk_fma_f32 v[114:115], v[114:115], v[174:175], v[200:201]
	v_med3_f32 v162, v118, s95, v247
	v_med3_f32 v163, v119, s95, v247
	v_cvt_pk_f16_f32 v162, v162, v163
	v_med3_f32 v163, v120, s95, v247
	v_med3_f32 v164, v121, s95, v247
	s_waitcnt vmcnt(3)
	v_pk_fma_f32 v[142:143], v[110:111], v[178:179], v[142:143]
	v_pk_fma_f32 v[116:117], v[116:117], v[172:173], v[202:203]
	v_cvt_pk_f16_f32 v163, v163, v164
	v_med3_f32 v164, v114, s95, v247
	v_med3_f32 v165, v115, s95, v247
	v_pk_fma_f32 v[144:145], v[112:113], v[176:177], v[144:145]
	v_pk_fma_f32 v[138:139], v[106:107], v[170:171], v[138:139]
	v_med3_f32 v106, v142, s95, v247
	v_med3_f32 v107, v143, s95, v247
	s_waitcnt vmcnt(1)
	v_pk_fma_f32 v[134:135], v[102:103], v[182:183], v[134:135]
	v_cvt_pk_f16_f32 v164, v164, v165
	v_med3_f32 v165, v116, s95, v247
	v_med3_f32 v187, v117, s95, v247
	v_pk_fma_f32 v[140:141], v[108:109], v[168:169], v[140:141]
	v_cvt_pk_f16_f32 v106, v106, v107
	v_med3_f32 v107, v144, s95, v247
	v_med3_f32 v108, v145, s95, v247
	v_pk_fma_f32 v[136:137], v[104:105], v[180:181], v[136:137]
	v_pk_fma_f32 v[130:131], v[98:99], v[174:175], v[130:131]
	v_med3_f32 v98, v134, s95, v247
	v_med3_f32 v99, v135, s95, v247
	v_cvt_pk_f16_f32 v165, v165, v187
	v_cvt_pk_f16_f32 v107, v107, v108
	v_med3_f32 v108, v138, s95, v247
	v_med3_f32 v109, v139, s95, v247
	v_pk_fma_f32 v[132:133], v[100:101], v[172:173], v[132:133]
	v_cvt_pk_f16_f32 v98, v98, v99
	v_med3_f32 v99, v136, s95, v247
	v_med3_f32 v100, v137, s95, v247
	global_store_dwordx4 v[166:167], v[162:165], off offset:256
	v_cvt_pk_f16_f32 v108, v108, v109
	v_med3_f32 v109, v140, s95, v247
	v_lshlrev_b64 v[162:163], 11, v[208:209]
	v_med3_f32 v110, v141, s95, v247
	v_cvt_pk_f16_f32 v99, v99, v100
	v_med3_f32 v100, v130, s95, v247
	v_med3_f32 v101, v131, s95, v247
	v_cvt_pk_f16_f32 v109, v109, v110
	v_lshl_add_u64 v[110:111], s[26:27], 0, v[162:163]
	v_cvt_pk_f16_f32 v100, v100, v101
	v_med3_f32 v101, v132, s95, v247
	v_med3_f32 v102, v133, s95, v247
	v_add_u32_e32 v164, 32, v186
	v_lshl_add_u64 v[110:111], v[110:111], 0, v[122:123]
	v_cvt_pk_f16_f32 v101, v101, v102
	v_ashrrev_i32_e32 v165, 31, v164
	global_store_dwordx4 v[110:111], v[106:109], off
	global_store_dwordx4 v[110:111], v[98:101], off offset:256
	v_add_u32_e32 v166, 48, v186
	v_ashrrev_i32_e32 v167, 31, v166
	v_lshlrev_b64 v[98:99], 12, v[164:165]
	v_lshl_add_u64 v[98:99], v[184:185], 0, v[98:99]
	global_load_dwordx4 v[196:199], v[98:99], off offset:16
	global_load_dwordx4 v[200:203], v[98:99], off
	global_load_dwordx4 v[204:207], v[98:99], off offset:528
	global_load_dwordx4 v[208:211], v[98:99], off offset:512
	v_lshlrev_b64 v[98:99], 12, v[166:167]
	v_lshl_add_u64 v[102:103], v[184:185], 0, v[98:99]
	global_load_dwordx4 v[106:109], v[102:103], off offset:16
	global_load_dwordx4 v[110:113], v[102:103], off
	global_load_dwordx4 v[98:101], v[102:103], off offset:528
	s_nop 0
	global_load_dwordx4 v[102:105], v[102:103], off offset:512
	v_lshlrev_b64 v[166:167], 11, v[166:167]
	v_lshlrev_b64 v[164:165], 11, v[164:165]
	s_waitcnt vmcnt(7)
	v_pk_fma_f32 v[90:91], v[90:91], v[170:171], v[196:197]
	s_waitcnt vmcnt(6)
	v_pk_fma_f32 v[94:95], v[94:95], v[178:179], v[200:201]
	v_pk_fma_f32 v[96:97], v[96:97], v[176:177], v[202:203]
	s_waitcnt vmcnt(3)
	v_pk_fma_f32 v[106:107], v[74:75], v[170:171], v[106:107]
	s_waitcnt vmcnt(2)
	v_pk_fma_f32 v[110:111], v[78:79], v[178:179], v[110:111]
	v_pk_fma_f32 v[80:81], v[80:81], v[176:177], v[112:113]
	v_med3_f32 v74, v110, s95, v247
	v_med3_f32 v75, v111, s95, v247
	v_pk_fma_f32 v[78:79], v[76:77], v[168:169], v[108:109]
	v_cvt_pk_f16_f32 v74, v74, v75
	v_med3_f32 v75, v80, s95, v247
	v_med3_f32 v76, v81, s95, v247
	v_med3_f32 v187, v94, s95, v247
	v_med3_f32 v195, v95, s95, v247
	v_cvt_pk_f16_f32 v75, v75, v76
	v_med3_f32 v76, v106, s95, v247
	v_med3_f32 v77, v107, s95, v247
	v_cvt_pk_f16_f32 v196, v187, v195
	v_med3_f32 v187, v96, s95, v247
	v_med3_f32 v195, v97, s95, v247
	v_cvt_pk_f16_f32 v76, v76, v77
	v_med3_f32 v77, v78, s95, v247
	v_med3_f32 v108, v79, s95, v247
	v_pk_fma_f32 v[92:93], v[92:93], v[168:169], v[198:199]
	v_cvt_pk_f16_f32 v197, v187, v195
	v_med3_f32 v187, v90, s95, v247
	v_med3_f32 v195, v91, s95, v247
	v_cvt_pk_f16_f32 v77, v77, v108
	v_lshl_add_u64 v[108:109], s[26:27], 0, v[166:167]
	v_cvt_pk_f16_f32 v198, v187, v195
	v_med3_f32 v187, v92, s95, v247
	v_med3_f32 v195, v93, s95, v247
	v_lshl_add_u64 v[200:201], s[26:27], 0, v[164:165]
	v_pk_fma_f32 v[86:87], v[86:87], v[182:183], v[208:209]
	v_lshl_add_u64 v[108:109], v[108:109], 0, v[122:123]
	s_waitcnt vmcnt(0)
	v_pk_fma_f32 v[102:103], v[70:71], v[182:183], v[102:103]
	v_cvt_pk_f16_f32 v199, v187, v195
	v_lshl_add_u64 v[200:201], v[200:201], 0, v[122:123]
	v_pk_fma_f32 v[88:89], v[88:89], v[180:181], v[210:211]
	v_med3_f32 v187, v86, s95, v247
	v_med3_f32 v195, v87, s95, v247
	global_store_dwordx4 v[108:109], v[74:77], off
	v_pk_fma_f32 v[98:99], v[66:67], v[174:175], v[98:99]
	v_med3_f32 v66, v102, s95, v247
	v_pk_fma_f32 v[76:77], v[72:73], v[180:181], v[104:105]
	v_med3_f32 v67, v103, s95, v247
	global_store_dwordx4 v[200:201], v[196:199], off
	v_pk_fma_f32 v[82:83], v[82:83], v[174:175], v[204:205]
	v_pk_fma_f32 v[74:75], v[68:69], v[172:173], v[100:101]
	v_cvt_pk_f16_f32 v196, v187, v195
	v_med3_f32 v187, v88, s95, v247
	v_med3_f32 v195, v89, s95, v247
	v_cvt_pk_f16_f32 v66, v66, v67
	v_med3_f32 v67, v76, s95, v247
	v_med3_f32 v68, v77, s95, v247
	v_pk_fma_f32 v[84:85], v[84:85], v[172:173], v[206:207]
	v_cvt_pk_f16_f32 v197, v187, v195
	v_med3_f32 v187, v82, s95, v247
	v_med3_f32 v195, v83, s95, v247
	v_cvt_pk_f16_f32 v67, v67, v68
	v_med3_f32 v68, v98, s95, v247
	v_med3_f32 v69, v99, s95, v247
	v_cvt_pk_f16_f32 v198, v187, v195
	v_med3_f32 v187, v84, s95, v247
	v_med3_f32 v195, v85, s95, v247
	v_cvt_pk_f16_f32 v68, v68, v69
	v_med3_f32 v69, v74, s95, v247
	v_med3_f32 v70, v75, s95, v247
	v_add_u32_e32 v100, 0x80, v186
	v_cvt_pk_f16_f32 v199, v187, v195
	v_cvt_pk_f16_f32 v69, v69, v70
	v_ashrrev_i32_e32 v101, 31, v100
	global_store_dwordx4 v[200:201], v[196:199], off offset:256
	global_store_dwordx4 v[108:109], v[66:69], off offset:256
	v_add_u32_e32 v104, 0x90, v186
	v_ashrrev_i32_e32 v105, 31, v104
	v_lshlrev_b64 v[66:67], 12, v[100:101]
	v_lshl_add_u64 v[66:67], v[184:185], 0, v[66:67]
	global_load_dwordx4 v[196:199], v[66:67], off offset:16
	global_load_dwordx4 v[200:203], v[66:67], off
	global_load_dwordx4 v[204:207], v[66:67], off offset:528
	global_load_dwordx4 v[208:211], v[66:67], off offset:512
	v_lshlrev_b64 v[66:67], 12, v[104:105]
	v_lshl_add_u64 v[70:71], v[184:185], 0, v[66:67]
	global_load_dwordx4 v[212:215], v[70:71], off offset:16
	global_load_dwordx4 v[216:219], v[70:71], off
	global_load_dwordx4 v[66:69], v[70:71], off offset:528
	s_nop 0
	global_load_dwordx4 v[70:73], v[70:71], off offset:512
	v_lshlrev_b64 v[100:101], 11, v[100:101]
	v_lshlrev_b64 v[104:105], 11, v[104:105]
	s_waitcnt vmcnt(7)
	v_pk_fma_f32 v[58:59], v[58:59], v[170:171], v[196:197]
	s_waitcnt vmcnt(6)
	v_pk_fma_f32 v[62:63], v[62:63], v[178:179], v[200:201]
	v_pk_fma_f32 v[64:65], v[64:65], v[176:177], v[202:203]
	v_med3_f32 v108, v62, s95, v247
	v_med3_f32 v109, v63, s95, v247
	v_cvt_pk_f16_f32 v196, v108, v109
	v_med3_f32 v108, v64, s95, v247
	v_med3_f32 v109, v65, s95, v247
	v_pk_fma_f32 v[60:61], v[60:61], v[168:169], v[198:199]
	v_cvt_pk_f16_f32 v197, v108, v109
	v_med3_f32 v108, v58, s95, v247
	v_med3_f32 v109, v59, s95, v247
	v_cvt_pk_f16_f32 v198, v108, v109
	v_med3_f32 v108, v60, s95, v247
	v_med3_f32 v109, v61, s95, v247
	v_cvt_pk_f16_f32 v199, v108, v109
	v_lshl_add_u64 v[108:109], s[26:27], 0, v[100:101]
	s_waitcnt vmcnt(4)
	v_pk_fma_f32 v[54:55], v[54:55], v[182:183], v[208:209]
	v_lshl_add_u64 v[108:109], v[108:109], 0, v[122:123]
	v_pk_fma_f32 v[56:57], v[56:57], v[180:181], v[210:211]
	v_med3_f32 v112, v54, s95, v247
	v_med3_f32 v113, v55, s95, v247
	global_store_dwordx4 v[108:109], v[196:199], off
	v_pk_fma_f32 v[50:51], v[50:51], v[174:175], v[204:205]
	v_pk_fma_f32 v[52:53], v[52:53], v[172:173], v[206:207]
	v_cvt_pk_f16_f32 v196, v112, v113
	v_med3_f32 v112, v56, s95, v247
	v_med3_f32 v113, v57, s95, v247
	v_cvt_pk_f16_f32 v197, v112, v113
	v_med3_f32 v112, v50, s95, v247
	v_med3_f32 v113, v51, s95, v247
	v_cvt_pk_f16_f32 v198, v112, v113
	v_med3_f32 v112, v52, s95, v247
	v_med3_f32 v113, v53, s95, v247
	v_cvt_pk_f16_f32 v199, v112, v113
	s_waitcnt vmcnt(3)
	v_pk_fma_f32 v[112:113], v[46:47], v[178:179], v[216:217]
	global_store_dwordx4 v[108:109], v[196:199], off offset:256
	v_pk_fma_f32 v[48:49], v[48:49], v[176:177], v[218:219]
	v_pk_fma_f32 v[108:109], v[42:43], v[170:171], v[212:213]
	v_med3_f32 v42, v112, s95, v247
	v_med3_f32 v43, v113, s95, v247
	v_cvt_pk_f16_f32 v196, v42, v43
	v_med3_f32 v42, v48, s95, v247
	v_med3_f32 v43, v49, s95, v247
	v_pk_fma_f32 v[44:45], v[44:45], v[168:169], v[214:215]
	v_cvt_pk_f16_f32 v197, v42, v43
	v_med3_f32 v42, v108, s95, v247
	v_med3_f32 v43, v109, s95, v247
	v_cvt_pk_f16_f32 v198, v42, v43
	v_med3_f32 v42, v44, s95, v247
	v_med3_f32 v43, v45, s95, v247
	v_cvt_pk_f16_f32 v199, v42, v43
	v_lshl_add_u64 v[42:43], s[26:27], 0, v[104:105]
	s_waitcnt vmcnt(2)
	v_pk_fma_f32 v[46:47], v[38:39], v[182:183], v[70:71]
	v_lshl_add_u64 v[200:201], v[42:43], 0, v[122:123]
	v_pk_fma_f32 v[40:41], v[40:41], v[180:181], v[72:73]
	v_pk_fma_f32 v[42:43], v[34:35], v[174:175], v[66:67]
	v_med3_f32 v34, v46, s95, v247
	v_med3_f32 v35, v47, s95, v247
	v_pk_fma_f32 v[38:39], v[36:37], v[172:173], v[68:69]
	v_cvt_pk_f16_f32 v34, v34, v35
	v_med3_f32 v35, v40, s95, v247
	v_med3_f32 v36, v41, s95, v247
	v_cvt_pk_f16_f32 v35, v35, v36
	v_med3_f32 v36, v42, s95, v247
	v_med3_f32 v37, v43, s95, v247
	v_cvt_pk_f16_f32 v36, v36, v37
	v_med3_f32 v37, v38, s95, v247
	v_med3_f32 v66, v39, s95, v247
	v_cvt_pk_f16_f32 v37, v37, v66
	v_add_u32_e32 v66, 0xa0, v186
	v_ashrrev_i32_e32 v67, 31, v66
	global_store_dwordx4 v[200:201], v[196:199], off
	global_store_dwordx4 v[200:201], v[34:37], off offset:256
	v_add_u32_e32 v72, 0xb0, v186
	v_ashrrev_i32_e32 v73, 31, v72
	v_lshlrev_b64 v[34:35], 12, v[66:67]
	v_lshl_add_u64 v[34:35], v[184:185], 0, v[34:35]
	global_load_dwordx4 v[68:71], v[34:35], off offset:16
	global_load_dwordx4 v[196:199], v[34:35], off
	global_load_dwordx4 v[200:203], v[34:35], off offset:528
	global_load_dwordx4 v[204:207], v[34:35], off offset:512
	v_lshlrev_b64 v[34:35], 12, v[72:73]
	v_lshl_add_u64 v[212:213], v[184:185], 0, v[34:35]
	global_load_dwordx4 v[184:187], v[212:213], off offset:16
	global_load_dwordx4 v[208:211], v[212:213], off
	global_load_dwordx4 v[34:37], v[212:213], off offset:528
	s_nop 0
	global_load_dwordx4 v[212:215], v[212:213], off offset:512
	v_lshlrev_b64 v[66:67], 11, v[66:67]
	s_waitcnt vmcnt(7)
	v_pk_fma_f32 v[26:27], v[26:27], v[170:171], v[68:69]
	s_waitcnt vmcnt(6)
	v_pk_fma_f32 v[30:31], v[30:31], v[178:179], v[196:197]
	v_pk_fma_f32 v[32:33], v[32:33], v[176:177], v[198:199]
	v_med3_f32 v68, v30, s95, v247
	v_med3_f32 v69, v31, s95, v247
	v_pk_fma_f32 v[28:29], v[28:29], v[168:169], v[70:71]
	v_cvt_pk_f16_f32 v68, v68, v69
	v_med3_f32 v69, v32, s95, v247
	v_med3_f32 v70, v33, s95, v247
	v_cvt_pk_f16_f32 v69, v69, v70
	v_med3_f32 v70, v26, s95, v247
	v_med3_f32 v71, v27, s95, v247
	v_cvt_pk_f16_f32 v70, v70, v71
	v_med3_f32 v71, v28, s95, v247
	v_med3_f32 v195, v29, s95, v247
	v_lshl_add_u64 v[196:197], s[26:27], 0, v[66:67]
	v_cvt_pk_f16_f32 v71, v71, v195
	v_lshl_add_u64 v[196:197], v[196:197], 0, v[122:123]
	s_waitcnt vmcnt(4)
	v_pk_fma_f32 v[22:23], v[22:23], v[182:183], v[204:205]
	global_store_dwordx4 v[196:197], v[68:71], off
	v_pk_fma_f32 v[24:25], v[24:25], v[180:181], v[206:207]
	v_pk_fma_f32 v[18:19], v[18:19], v[174:175], v[200:201]
	v_med3_f32 v68, v22, s95, v247
	v_med3_f32 v69, v23, s95, v247
	v_cvt_pk_f16_f32 v68, v68, v69
	v_med3_f32 v69, v24, s95, v247
	v_med3_f32 v70, v25, s95, v247
	v_pk_fma_f32 v[20:21], v[20:21], v[172:173], v[202:203]
	v_cvt_pk_f16_f32 v69, v69, v70
	v_med3_f32 v70, v18, s95, v247
	v_med3_f32 v71, v19, s95, v247
	v_cvt_pk_f16_f32 v70, v70, v71
	v_med3_f32 v71, v20, s95, v247
	v_med3_f32 v195, v21, s95, v247
	v_cvt_pk_f16_f32 v71, v71, v195
	s_waitcnt vmcnt(3)
	v_pk_fma_f32 v[178:179], v[14:15], v[178:179], v[208:209]
	global_store_dwordx4 v[196:197], v[68:71], off offset:256
	v_pk_fma_f32 v[176:177], v[16:17], v[176:177], v[210:211]
	v_pk_fma_f32 v[170:171], v[10:11], v[170:171], v[184:185]
	v_lshlrev_b64 v[68:69], 11, v[72:73]
	v_pk_fma_f32 v[72:73], v[12:13], v[168:169], v[186:187]
	v_med3_f32 v10, v178, s95, v247
	v_med3_f32 v11, v179, s95, v247
	s_waitcnt vmcnt(2)
	v_pk_fma_f32 v[168:169], v[6:7], v[182:183], v[212:213]
	v_cvt_pk_f16_f32 v10, v10, v11
	v_med3_f32 v11, v176, s95, v247
	v_med3_f32 v12, v177, s95, v247
	v_pk_fma_f32 v[70:71], v[8:9], v[180:181], v[214:215]
	v_pk_fma_f32 v[34:35], v[2:3], v[174:175], v[34:35]
	v_med3_f32 v2, v168, s95, v247
	v_med3_f32 v3, v169, s95, v247
	v_cvt_pk_f16_f32 v11, v11, v12
	v_med3_f32 v12, v170, s95, v247
	v_med3_f32 v13, v171, s95, v247
	v_pk_fma_f32 v[36:37], v[4:5], v[172:173], v[36:37]
	v_cvt_pk_f16_f32 v2, v2, v3
	v_med3_f32 v3, v70, s95, v247
	v_med3_f32 v4, v71, s95, v247
	v_cvt_pk_f16_f32 v12, v12, v13
	v_med3_f32 v13, v72, s95, v247
	v_med3_f32 v14, v73, s95, v247
	v_cvt_pk_f16_f32 v3, v3, v4
	v_med3_f32 v4, v34, s95, v247
	v_med3_f32 v5, v35, s95, v247
	v_cvt_pk_f16_f32 v13, v13, v14
	v_lshl_add_u64 v[14:15], s[26:27], 0, v[68:69]
	v_cvt_pk_f16_f32 v4, v4, v5
	v_med3_f32 v5, v36, s95, v247
	v_med3_f32 v6, v37, s95, v247
	v_lshl_add_u64 v[14:15], v[14:15], 0, v[122:123]
	v_cvt_pk_f16_f32 v5, v5, v6
	global_store_dwordx4 v[14:15], v[2:5], off offset:256
	global_store_dwordx4 v[14:15], v[10:13], off
	s_nop 0
	v_mul_f32_e32 v2, v161, v161
	v_mul_f32_e32 v3, v129, v129
	v_fmac_f32_e32 v2, v160, v160
	v_fmac_f32_e32 v3, v128, v128
	v_add_f32_e32 v2, v2, v3
	v_mul_f32_e32 v3, v127, v127
	v_mul_f32_e32 v4, v125, v125
	v_fmac_f32_e32 v3, v126, v126
	v_fmac_f32_e32 v4, v124, v124
	v_add_f32_e32 v3, v3, v4
	v_add_f32_e32 v2, v2, v3
	v_mul_f32_e32 v3, v119, v119
	v_mul_f32_e32 v4, v121, v121
	v_fmac_f32_e32 v3, v118, v118
	v_fmac_f32_e32 v4, v120, v120
	v_add_f32_e32 v3, v3, v4
	v_add_f32_e32 v2, v2, v3
	v_mul_f32_e32 v3, v115, v115
	v_mul_f32_e32 v4, v117, v117
	v_fmac_f32_e32 v3, v114, v114
	v_fmac_f32_e32 v4, v116, v116
	v_add_f32_e32 v3, v3, v4
	v_add_f32_e32 v2, v2, v3
	v_mov_b32_e32 v3, v2
	s_nop 1
	v_permlane16_swap_b32_e32 v3, v2
	s_waitcnt lgkmcnt(0)
	v_add_f32_e32 v3, v2, v3
	v_mov_b32_e32 v4, v3
	s_nop 1
	v_permlane32_swap_b32_e32 v3, v4
	v_lshl_add_u32 v2, v193, 4, s86
	s_and_saveexec_b64 s[0:1], vcc
	v_add_f32_e32 v3, v3, v4
	ds_write_b32 v2, v3
	s_or_b64 exec, exec, s[0:1]
	v_mul_f32_e32 v3, v143, v143
	v_mul_f32_e32 v4, v145, v145
	v_fmac_f32_e32 v3, v142, v142
	v_fmac_f32_e32 v4, v144, v144
	v_add_f32_e32 v3, v3, v4
	v_mul_f32_e32 v4, v139, v139
	v_mul_f32_e32 v5, v141, v141
	v_fmac_f32_e32 v4, v138, v138
	v_fmac_f32_e32 v5, v140, v140
	v_add_f32_e32 v4, v4, v5
	v_add_f32_e32 v3, v3, v4
	v_mul_f32_e32 v4, v135, v135
	v_mul_f32_e32 v5, v137, v137
	v_fmac_f32_e32 v4, v134, v134
	v_fmac_f32_e32 v5, v136, v136
	v_add_f32_e32 v4, v4, v5
	v_add_f32_e32 v3, v3, v4
	v_mul_f32_e32 v4, v131, v131
	v_mul_f32_e32 v5, v133, v133
	v_fmac_f32_e32 v4, v130, v130
	v_fmac_f32_e32 v5, v132, v132
	v_add_f32_e32 v4, v4, v5
	v_add_f32_e32 v3, v3, v4
	v_mov_b32_e32 v4, v3
	s_nop 1
	v_permlane16_swap_b32_e32 v4, v3
	s_waitcnt lgkmcnt(0)
	v_add_f32_e32 v3, v3, v4
	v_mov_b32_e32 v4, v3
	s_nop 1
	v_permlane32_swap_b32_e32 v3, v4
	s_and_saveexec_b64 s[0:1], vcc
	v_add_f32_e32 v3, v3, v4
	ds_write_b32 v2, v3 offset:256
	s_or_b64 exec, exec, s[0:1]
	v_mul_f32_e32 v3, v95, v95
	v_mul_f32_e32 v4, v97, v97
	v_fmac_f32_e32 v3, v94, v94
	v_fmac_f32_e32 v4, v96, v96
	v_add_f32_e32 v3, v3, v4
	v_mul_f32_e32 v4, v91, v91
	v_mul_f32_e32 v5, v93, v93
	v_fmac_f32_e32 v4, v90, v90
	v_fmac_f32_e32 v5, v92, v92
	v_add_f32_e32 v4, v4, v5
	v_add_f32_e32 v3, v3, v4
	v_mul_f32_e32 v4, v87, v87
	v_mul_f32_e32 v5, v89, v89
	v_fmac_f32_e32 v4, v86, v86
	v_fmac_f32_e32 v5, v88, v88
	v_add_f32_e32 v4, v4, v5
	v_add_f32_e32 v3, v3, v4
	v_mul_f32_e32 v4, v83, v83
	v_mul_f32_e32 v5, v85, v85
	v_fmac_f32_e32 v4, v82, v82
	v_fmac_f32_e32 v5, v84, v84
	v_add_f32_e32 v4, v4, v5
	v_add_f32_e32 v3, v3, v4
	v_mov_b32_e32 v4, v3
	s_nop 1
	v_permlane16_swap_b32_e32 v4, v3
	s_waitcnt lgkmcnt(0)
	v_add_f32_e32 v3, v3, v4
	v_mov_b32_e32 v4, v3
	s_nop 1
	v_permlane32_swap_b32_e32 v3, v4
	s_and_saveexec_b64 s[0:1], vcc
	v_add_f32_e32 v3, v3, v4
	ds_write_b32 v2, v3 offset:512
	s_or_b64 exec, exec, s[0:1]
	v_mul_f32_e32 v3, v111, v111
	v_mul_f32_e32 v4, v81, v81
	v_fmac_f32_e32 v3, v110, v110
	v_fmac_f32_e32 v4, v80, v80
	v_add_f32_e32 v3, v3, v4
	v_mul_f32_e32 v4, v107, v107
	v_mul_f32_e32 v5, v79, v79
	v_fmac_f32_e32 v4, v106, v106
	v_fmac_f32_e32 v5, v78, v78
	v_add_f32_e32 v4, v4, v5
	v_add_f32_e32 v3, v3, v4
	v_mul_f32_e32 v4, v103, v103
	v_mul_f32_e32 v5, v77, v77
	v_fmac_f32_e32 v4, v102, v102
	v_fmac_f32_e32 v5, v76, v76
	v_add_f32_e32 v4, v4, v5
	v_add_f32_e32 v3, v3, v4
	v_mul_f32_e32 v4, v99, v99
	v_mul_f32_e32 v5, v75, v75
	v_fmac_f32_e32 v4, v98, v98
	v_fmac_f32_e32 v5, v74, v74
	v_add_f32_e32 v4, v4, v5
	v_add_f32_e32 v3, v3, v4
	v_mov_b32_e32 v4, v3
	s_nop 1
	v_permlane16_swap_b32_e32 v4, v3
	s_waitcnt lgkmcnt(0)
	v_add_f32_e32 v3, v3, v4
	v_mov_b32_e32 v4, v3
	s_nop 1
	v_permlane32_swap_b32_e32 v3, v4
	s_and_saveexec_b64 s[0:1], vcc
	v_add_f32_e32 v3, v3, v4
	ds_write_b32 v2, v3 offset:768
	s_or_b64 exec, exec, s[0:1]
	v_mul_f32_e32 v3, v63, v63
	v_mul_f32_e32 v4, v65, v65
	v_fmac_f32_e32 v3, v62, v62
	v_fmac_f32_e32 v4, v64, v64
	v_add_f32_e32 v3, v3, v4
	v_mul_f32_e32 v4, v59, v59
	v_mul_f32_e32 v5, v61, v61
	v_fmac_f32_e32 v4, v58, v58
	v_fmac_f32_e32 v5, v60, v60
	v_add_f32_e32 v4, v4, v5
	v_add_f32_e32 v3, v3, v4
	v_mul_f32_e32 v4, v55, v55
	v_mul_f32_e32 v5, v57, v57
	v_fmac_f32_e32 v4, v54, v54
	v_fmac_f32_e32 v5, v56, v56
	v_add_f32_e32 v4, v4, v5
	v_add_f32_e32 v3, v3, v4
	v_mul_f32_e32 v4, v51, v51
	v_mul_f32_e32 v5, v53, v53
	v_fmac_f32_e32 v4, v50, v50
	v_fmac_f32_e32 v5, v52, v52
	v_add_f32_e32 v4, v4, v5
	v_add_f32_e32 v3, v3, v4
	v_mov_b32_e32 v4, v3
	s_nop 1
	v_permlane16_swap_b32_e32 v4, v3
	s_waitcnt lgkmcnt(0)
	v_add_f32_e32 v3, v3, v4
	v_mov_b32_e32 v4, v3
	s_nop 1
	v_permlane32_swap_b32_e32 v3, v4
	s_and_saveexec_b64 s[0:1], vcc
	v_add_f32_e32 v3, v3, v4
	ds_write_b32 v2, v3 offset:2048
	s_or_b64 exec, exec, s[0:1]
	v_mul_f32_e32 v3, v113, v113
	v_mul_f32_e32 v4, v49, v49
	v_fmac_f32_e32 v3, v112, v112
	v_fmac_f32_e32 v4, v48, v48
	v_add_f32_e32 v3, v3, v4
	v_mul_f32_e32 v4, v109, v109
	v_mul_f32_e32 v5, v45, v45
	v_fmac_f32_e32 v4, v108, v108
	v_fmac_f32_e32 v5, v44, v44
	v_add_f32_e32 v4, v4, v5
	v_add_f32_e32 v3, v3, v4
	v_mul_f32_e32 v4, v47, v47
	v_mul_f32_e32 v5, v41, v41
	v_fmac_f32_e32 v4, v46, v46
	v_fmac_f32_e32 v5, v40, v40
	v_add_f32_e32 v4, v4, v5
	v_add_f32_e32 v3, v3, v4
	v_mul_f32_e32 v4, v43, v43
	v_mul_f32_e32 v5, v39, v39
	v_fmac_f32_e32 v4, v42, v42
	v_fmac_f32_e32 v5, v38, v38
	v_add_f32_e32 v4, v4, v5
	v_add_f32_e32 v3, v3, v4
	v_mov_b32_e32 v4, v3
	s_nop 1
	v_permlane16_swap_b32_e32 v4, v3
	s_waitcnt lgkmcnt(0)
	v_add_f32_e32 v3, v3, v4
	v_mov_b32_e32 v4, v3
	s_nop 1
	v_permlane32_swap_b32_e32 v3, v4
	s_and_saveexec_b64 s[0:1], vcc
	v_add_f32_e32 v3, v3, v4
	ds_write_b32 v2, v3 offset:2304
	s_or_b64 exec, exec, s[0:1]
	v_mul_f32_e32 v3, v31, v31
	v_mul_f32_e32 v4, v33, v33
	v_fmac_f32_e32 v3, v30, v30
	v_fmac_f32_e32 v4, v32, v32
	v_add_f32_e32 v3, v3, v4
	v_mul_f32_e32 v4, v27, v27
	v_mul_f32_e32 v5, v29, v29
	v_fmac_f32_e32 v4, v26, v26
	v_fmac_f32_e32 v5, v28, v28
	v_add_f32_e32 v4, v4, v5
	v_add_f32_e32 v3, v3, v4
	v_mul_f32_e32 v4, v23, v23
	v_mul_f32_e32 v5, v25, v25
	v_fmac_f32_e32 v4, v22, v22
	v_fmac_f32_e32 v5, v24, v24
	v_add_f32_e32 v4, v4, v5
	v_add_f32_e32 v3, v3, v4
	v_mul_f32_e32 v4, v19, v19
	v_mul_f32_e32 v5, v21, v21
	v_fmac_f32_e32 v4, v18, v18
	v_fmac_f32_e32 v5, v20, v20
	v_add_f32_e32 v4, v4, v5
	v_add_f32_e32 v3, v3, v4
	v_mov_b32_e32 v4, v3
	s_nop 1
	v_permlane16_swap_b32_e32 v4, v3
	s_waitcnt lgkmcnt(0)
	v_add_f32_e32 v3, v3, v4
	v_mov_b32_e32 v4, v3
	s_nop 1
	v_permlane32_swap_b32_e32 v3, v4
	s_and_saveexec_b64 s[0:1], vcc
	v_add_f32_e32 v3, v3, v4
	ds_write_b32 v2, v3 offset:2560
	s_or_b64 exec, exec, s[0:1]
	v_mul_f32_e32 v3, v179, v179
	v_mul_f32_e32 v4, v177, v177
	v_fmac_f32_e32 v3, v178, v178
	v_fmac_f32_e32 v4, v176, v176
	v_add_f32_e32 v3, v3, v4
	v_mul_f32_e32 v4, v171, v171
	v_mul_f32_e32 v5, v73, v73
	v_fmac_f32_e32 v4, v170, v170
	v_fmac_f32_e32 v5, v72, v72
	v_add_f32_e32 v4, v4, v5
	v_add_f32_e32 v3, v3, v4
	v_mul_f32_e32 v4, v169, v169
	v_mul_f32_e32 v5, v71, v71
	v_fmac_f32_e32 v4, v168, v168
	v_fmac_f32_e32 v5, v70, v70
	v_add_f32_e32 v4, v4, v5
	v_add_f32_e32 v3, v3, v4
	v_mul_f32_e32 v4, v35, v35
	v_mul_f32_e32 v5, v37, v37
	v_fmac_f32_e32 v4, v34, v34
	v_fmac_f32_e32 v5, v36, v36
	v_add_f32_e32 v4, v4, v5
	v_add_f32_e32 v3, v3, v4
	v_mov_b32_e32 v4, v3
	s_nop 1
	v_permlane16_swap_b32_e32 v4, v3
	s_waitcnt lgkmcnt(0)
	v_add_f32_e32 v3, v3, v4
	v_mov_b32_e32 v4, v3
	s_nop 1
	v_permlane32_swap_b32_e32 v3, v4
	s_and_saveexec_b64 s[0:1], vcc
	v_add_f32_e32 v3, v3, v4
	ds_write_b32 v2, v3 offset:2816
	s_or_b64 exec, exec, s[0:1]
	v_lshl_add_u32 v5, v194, 4, v193
	s_waitcnt lgkmcnt(0)
	s_barrier
	v_and_or_b32 v4, v5, 31, s75
	v_add_u32_e32 v2, s2, v4
	v_cmp_gt_i32_e64 s[6:7], 32, v5
	v_ashrrev_i32_e32 v3, 31, v2
	s_and_saveexec_b64 s[0:1], s[6:7]
	s_cbranch_execz .LBB0_613
	v_lshl_add_u32 v6, v4, 4, 0
	v_add_u32_e32 v6, 0x20400, v6
	ds_read_b128 v[6:9], v6
	s_ashr_i32 s53, s52, 31
	s_waitcnt lgkmcnt(0)
	v_mov_b32_e32 v10, v7
	v_mov_b32_e32 v11, v8
	v_mov_b32_e32 v7, v9
	v_pk_add_f32 v[6:7], v[10:11], v[6:7]
	v_lshl_add_u64 v[8:9], v[2:3], 4, s[8:9]
	v_pk_add_f32 v[6:7], v[6:7], v[6:7] op_sel:[0,1] op_sel_hi:[1,0]
	v_lshl_add_u64 v[8:9], s[52:53], 2, v[8:9]
	global_store_dword v[8:9], v6, off sc1

.Lmy_nk_noreload:
	v_cvt_f32_f16_sdwa v43, v32 dst_sel:DWORD dst_unused:UNUSED_PAD src0_sel:WORD_1
	v_cvt_f32_f16_e32 v42, v32
	v_cvt_f32_f16_sdwa v41, v33 dst_sel:DWORD dst_unused:UNUSED_PAD src0_sel:WORD_1
	v_cvt_f32_f16_e32 v40, v33
	v_cvt_f32_f16_sdwa v45, v30 dst_sel:DWORD dst_unused:UNUSED_PAD src0_sel:WORD_1
	v_cvt_f32_f16_e32 v44, v30
	v_cvt_f32_f16_sdwa v47, v31 dst_sel:DWORD dst_unused:UNUSED_PAD src0_sel:WORD_1
	v_cvt_f32_f16_e32 v46, v31
	v_cvt_f32_f16_sdwa v37, v26 dst_sel:DWORD dst_unused:UNUSED_PAD src0_sel:WORD_1
	v_cvt_f32_f16_e32 v36, v26
	v_pk_mul_f32 v[32:33], v[42:43], v[42:43]
	v_pk_mul_f32 v[34:35], v[40:41], v[40:41]
	v_pk_mul_f32 v[48:49], v[44:45], v[44:45]
	v_pk_mul_f32 v[50:51], v[46:47], v[46:47]
	v_pk_mul_f32 v[52:53], v[36:37], v[36:37]
	v_add_f32_e32 v50, v50, v51
	v_add_f32_e32 v48, v48, v49
	v_add_f32_e32 v34, v34, v35
	v_add_f32_e32 v32, v32, v33
	v_add_f32_e32 v48, v48, v50
	v_add_f32_e32 v32, v32, v34
	v_add_f32_e32 v34, v52, v53
	v_cvt_f32_f16_sdwa v39, v27 dst_sel:DWORD dst_unused:UNUSED_PAD src0_sel:WORD_1
	v_cvt_f32_f16_e32 v38, v27
	v_cvt_f32_f16_sdwa v27, v28 dst_sel:DWORD dst_unused:UNUSED_PAD src0_sel:WORD_1
	v_cvt_f32_f16_e32 v26, v28
	v_cvt_f32_f16_sdwa v31, v29 dst_sel:DWORD dst_unused:UNUSED_PAD src0_sel:WORD_1
	v_cvt_f32_f16_e32 v30, v29
	v_pk_mul_f32 v[54:55], v[38:39], v[38:39]
	v_pk_mul_f32 v[28:29], v[26:27], v[26:27]
	v_add_f32_e32 v33, v54, v55
	v_pk_mul_f32 v[58:59], v[30:31], v[30:31]
	v_add_f32_e32 v32, v32, v48
	v_add_f32_e32 v33, v34, v33
	v_add_f32_e32 v32, v33, v32
	v_add_f32_e32 v33, v58, v59
	v_add_f32_e32 v28, v28, v29
	v_add_f32_e32 v28, v28, v33
	v_add_f32_e32 v28, v28, v32
	ds_swizzle_b32 v29, v28 offset:swizzle(SWAP,1)
	s_ashr_i32 s2, s50, 13
	v_mad_i64_i32 v[48:49], s[0:1], s2, v252, v[8:9]
	v_lshl_add_u64 v[34:35], s[52:53], 0, v[0:1]
	s_waitcnt lgkmcnt(0)
	v_add_f32_e32 v28, v28, v29
	ds_swizzle_b32 v29, v28 offset:swizzle(SWAP,2)
	s_ashr_i32 s3, s2, 31
	s_waitcnt lgkmcnt(0)
	v_add_f32_e32 v28, v28, v29
	ds_swizzle_b32 v29, v28 offset:swizzle(SWAP,4)
	s_waitcnt lgkmcnt(0)
	v_add_f32_e32 v28, v28, v29
	ds_swizzle_b32 v29, v28 offset:swizzle(SWAP,8)
	s_waitcnt lgkmcnt(0)
	v_add_f32_e32 v28, v28, v29
	v_mov_b32_e32 v29, v28
	s_nop 1
	v_permlane16_swap_b32_e32 v29, v28
	s_waitcnt lgkmcnt(0)
	v_add_f32_e32 v28, v28, v29
	v_mov_b32_e32 v29, v28
	s_nop 1
	v_permlane32_swap_b32_e32 v28, v29
	v_add_f32_e32 v28, v28, v29
	v_fmamk_f32 v28, v28, 0x3a800000, v244
	v_rsq_f32_e32 v32, v28
	v_mad_i64_i32 v[28:29], s[0:1], s2, v252, v[2:3]
	s_mov_b32 s0, 0x1b400000
	v_pk_mul_f32 v[40:41], v[40:41], v[32:33] op_sel_hi:[1,0]
	v_pk_mul_f32 v[42:43], v[42:43], v[32:33] op_sel_hi:[1,0]
	v_pk_mul_f32 v[46:47], v[46:47], v[32:33] op_sel_hi:[1,0]
	v_pk_mul_f32 v[44:45], v[44:45], v[32:33] op_sel_hi:[1,0]
	v_pk_mul_f32 v[38:39], v[38:39], v[32:33] op_sel_hi:[1,0]
	v_pk_mul_f32 v[36:37], v[36:37], v[32:33] op_sel_hi:[1,0]
	v_mov_b64_e32 v[50:51], v[100:101]
	v_mov_b64_e32 v[52:53], v[102:103]
	v_pk_mul_f32 v[54:55], v[50:51], v[42:43]
	v_pk_mul_f32 v[58:59], v[52:53], v[40:41]
	v_mov_b64_e32 v[50:51], v[104:105]
	v_mov_b64_e32 v[52:53], v[106:107]
	v_pk_add_f32 v[60:61], v[52:53], 1.0 op_sel_hi:[1,0]
	v_pk_add_f32 v[62:63], v[50:51], 1.0 op_sel_hi:[1,0]
	v_mov_b64_e32 v[50:51], v[108:109]
	v_mov_b64_e32 v[52:53], v[110:111]
	v_pk_fma_f32 v[50:51], v[62:63], v[54:55], v[50:51]
	v_add_co_u32_e32 v54, vcc, s0, v34
	v_pk_fma_f32 v[52:53], v[60:61], v[58:59], v[52:53]
	s_nop 0
	v_addc_co_u32_e32 v55, vcc, 0, v35, vcc
	v_cvt_pk_bf16_f32 v50, v50, v51
	v_cvt_pk_bf16_f32 v51, v52, v53
	global_store_dwordx2 v[54:55], v[50:51], off
	v_mov_b64_e32 v[50:51], v[112:113]
	v_mov_b64_e32 v[52:53], v[114:115]
	s_lshl_b64 s[0:1], s[2:3], 13
	v_pk_mul_f32 v[58:59], v[50:51], v[44:45]
	v_pk_mul_f32 v[60:61], v[52:53], v[46:47]
	v_mov_b64_e32 v[50:51], v[116:117]
	v_mov_b64_e32 v[52:53], v[118:119]
	v_pk_add_f32 v[62:63], v[52:53], 1.0 op_sel_hi:[1,0]
	v_pk_add_f32 v[64:65], v[50:51], 1.0 op_sel_hi:[1,0]
	v_mov_b64_e32 v[50:51], v[120:121]
	v_mov_b64_e32 v[52:53], v[122:123]
	v_pk_fma_f32 v[50:51], v[64:65], v[58:59], v[50:51]
	v_pk_fma_f32 v[52:53], v[62:63], v[60:61], v[52:53]
	v_cvt_pk_bf16_f32 v50, v50, v51
	s_nop 0
	v_cvt_pk_bf16_f32 v51, v52, v53
	global_store_dwordx2 v[54:55], v[50:51], off offset:512
	v_mov_b64_e32 v[50:51], v[124:125]
	v_mov_b64_e32 v[52:53], v[126:127]
	v_pk_mul_f32 v[58:59], v[36:37], v[50:51]
	v_pk_mul_f32 v[60:61], v[38:39], v[52:53]
	v_mov_b64_e32 v[50:51], v[128:129]
	v_mov_b64_e32 v[52:53], v[130:131]
	v_pk_add_f32 v[62:63], v[52:53], 1.0 op_sel_hi:[1,0]
	v_pk_add_f32 v[64:65], v[50:51], 1.0 op_sel_hi:[1,0]
	v_mov_b64_e32 v[50:51], v[132:133]
	v_mov_b64_e32 v[52:53], v[134:135]
	v_pk_fma_f32 v[50:51], v[58:59], v[64:65], v[50:51]
	v_pk_fma_f32 v[52:53], v[60:61], v[62:63], v[52:53]
	v_cvt_pk_bf16_f32 v50, v50, v51
	s_nop 0
	v_cvt_pk_bf16_f32 v51, v52, v53
	global_store_dwordx2 v[54:55], v[50:51], off offset:1024
	v_pk_mul_f32 v[50:51], v[30:31], v[32:33] op_sel_hi:[1,0]
	v_pk_mul_f32 v[52:53], v[26:27], v[32:33] op_sel_hi:[1,0]
	v_mov_b64_e32 v[30:31], v[136:137]
	v_mov_b64_e32 v[32:33], v[138:139]
	v_pk_mul_f32 v[58:59], v[52:53], v[30:31]
	v_pk_mul_f32 v[60:61], v[50:51], v[32:33]
	v_mov_b64_e32 v[30:31], v[140:141]
	v_mov_b64_e32 v[32:33], v[142:143]
	s_nop 0
	v_mov_b64_e32 v[26:27], v[144:145]
	v_mov_b64_e32 v[28:29], v[146:147]
	v_lshl_add_u64 v[48:49], v[4:5], 0, s[0:1]
	v_pk_add_f32 v[30:31], v[30:31], 1.0 op_sel_hi:[1,0]
	v_pk_add_f32 v[32:33], v[32:33], 1.0 op_sel_hi:[1,0]
	v_pk_fma_f32 v[26:27], v[58:59], v[30:31], v[26:27]
	v_pk_fma_f32 v[28:29], v[60:61], v[32:33], v[28:29]
	v_cvt_pk_bf16_f32 v26, v26, v27
	s_nop 0
	v_cvt_pk_bf16_f32 v27, v28, v29
	global_store_dwordx2 v[54:55], v[26:27], off offset:1536
	v_mov_b64_e32 v[26:27], v[148:149]
	v_mov_b64_e32 v[28:29], v[150:151]
	v_lshl_add_u64 v[54:55], v[10:11], 0, s[0:1]
	s_mov_b32 s0, 0x3400000
	v_pk_mul_f32 v[32:33], v[42:43], v[26:27]
	v_pk_mul_f32 v[40:41], v[40:41], v[28:29]
	v_mov_b64_e32 v[26:27], v[152:153]
	v_mov_b64_e32 v[28:29], v[154:155]
	v_pk_add_f32 v[42:43], v[28:29], 1.0 op_sel_hi:[1,0]
	v_mov_b64_e32 v[28:29], v[156:157]
	v_mov_b64_e32 v[30:31], v[158:159]
	v_pk_add_f32 v[58:59], v[26:27], 1.0 op_sel_hi:[1,0]
	v_pk_fma_f32 v[26:27], v[40:41], v[42:43], v[30:31]
	v_pk_fma_f32 v[28:29], v[32:33], v[58:59], v[28:29]
	v_add_co_u32_e32 v58, vcc, s0, v34
	v_cvt_pk_bf16_f32 v30, v28, v29
	v_cvt_pk_bf16_f32 v31, v26, v27
	s_nop 1
	v_addc_co_u32_e32 v59, vcc, 0, v35, vcc
	global_store_dwordx2 v[58:59], v[30:31], off
	v_mov_b64_e32 v[30:31], v[160:161]
	v_mov_b64_e32 v[32:33], v[162:163]
	v_pk_mul_f32 v[40:41], v[44:45], v[30:31]
	v_pk_mul_f32 v[42:43], v[46:47], v[32:33]
	v_mov_b64_e32 v[30:31], v[164:165]
	v_mov_b64_e32 v[32:33], v[166:167]
	v_pk_add_f32 v[44:45], v[32:33], 1.0 op_sel_hi:[1,0]
	v_mov_b64_e32 v[32:33], v[168:169]
	v_mov_b64_e32 v[34:35], v[170:171]
	v_pk_add_f32 v[46:47], v[30:31], 1.0 op_sel_hi:[1,0]
	v_pk_fma_f32 v[30:31], v[42:43], v[44:45], v[34:35]
	v_pk_fma_f32 v[32:33], v[40:41], v[46:47], v[32:33]
	s_nop 0
	v_cvt_pk_bf16_f32 v34, v32, v33
	v_cvt_pk_bf16_f32 v35, v30, v31
	global_store_dwordx2 v[58:59], v[34:35], off offset:512
	v_mov_b64_e32 v[40:41], v[172:173]
	v_mov_b64_e32 v[42:43], v[174:175]
	v_pk_mul_f32 v[40:41], v[36:37], v[40:41]
	v_mov_b64_e32 v[34:35], v[176:177]
	v_mov_b64_e32 v[36:37], v[178:179]
	v_pk_mul_f32 v[38:39], v[38:39], v[42:43]
	v_pk_add_f32 v[42:43], v[36:37], 1.0 op_sel_hi:[1,0]
	v_pk_add_f32 v[44:45], v[34:35], 1.0 op_sel_hi:[1,0]
	v_mov_b64_e32 v[34:35], v[180:181]
	v_mov_b64_e32 v[36:37], v[182:183]
	v_pk_fma_f32 v[38:39], v[38:39], v[42:43], v[36:37]
	v_pk_fma_f32 v[40:41], v[40:41], v[44:45], v[34:35]
	s_nop 0
	v_cvt_pk_bf16_f32 v34, v40, v41
	v_cvt_pk_bf16_f32 v35, v38, v39
	global_store_dwordx2 v[58:59], v[34:35], off offset:1024
	v_mov_b64_e32 v[34:35], v[184:185]
	v_mov_b64_e32 v[36:37], v[186:187]
	v_pk_mul_f32 v[46:47], v[52:53], v[34:35]
	v_pk_mul_f32 v[50:51], v[50:51], v[36:37]
	v_mov_b64_e32 v[34:35], v[188:189]
	v_mov_b64_e32 v[36:37], v[190:191]
	v_mov_b64_e32 v[42:43], v[192:193]
	v_mov_b64_e32 v[44:45], v[194:195]
	v_pk_add_f32 v[36:37], v[36:37], 1.0 op_sel_hi:[1,0]
	v_pk_add_f32 v[52:53], v[34:35], 1.0 op_sel_hi:[1,0]
	v_pk_fma_f32 v[34:35], v[50:51], v[36:37], v[44:45]
	v_pk_fma_f32 v[36:37], v[46:47], v[52:53], v[42:43]
	s_nop 0
	v_cvt_pk_bf16_f32 v42, v36, v37
	v_cvt_pk_bf16_f32 v43, v34, v35
	global_store_dwordx2 v[58:59], v[42:43], off offset:1536
	v_mbcnt_lo_u32_b32 v96, -1, 0
	v_mbcnt_hi_u32_b32 v96, -1, v96
	ds_read_b128 v[196:199], v56
	ds_read_b128 v[200:203], v56 offset:1024
	ds_read_b128 v[204:207], v56 offset:2048
	ds_read_b128 v[208:211], v56 offset:3072
	ds_read_b128 v[212:215], v56 offset:4096
	ds_read_b128 v[216:219], v56 offset:5120
	ds_read_b128 v[220:223], v56 offset:6144
	ds_read_b128 v[224:227], v56 offset:7168
	v_lshrrev_b32_e32 v97, 2, v96
	v_and_b32_e32 v98, 3, v96
	v_lshl_or_b32 v97, v97, 4, v98
	v_and_b32_e32 v97, 63, v97
	v_lshlrev_b32_e32 v97, 2, v97
	s_waitcnt lgkmcnt(4)
	v_mul_f32_e32 v228, v29, v197
	v_mul_f32_e32 v229, v27, v199
	v_mul_f32_e32 v230, v33, v201
	v_mul_f32_e32 v231, v31, v203
	v_mul_f32_e32 v232, v41, v205
	v_mul_f32_e32 v233, v39, v207
	v_mul_f32_e32 v234, v37, v209
	v_mul_f32_e32 v235, v35, v211
	v_fmac_f32_e32 v228, v28, v196
	v_fmac_f32_e32 v229, v26, v198
	v_fmac_f32_e32 v230, v32, v200
	v_fmac_f32_e32 v231, v30, v202
	v_fmac_f32_e32 v232, v40, v204
	v_fmac_f32_e32 v233, v38, v206
	v_fmac_f32_e32 v234, v36, v208
	v_fmac_f32_e32 v235, v34, v210
	v_add_f32_e32 v228, v228, v229
	v_add_f32_e32 v230, v230, v231
	v_add_f32_e32 v232, v232, v233
	v_add_f32_e32 v234, v234, v235
	v_add_f32_e32 v80, 0, v228
	v_add_f32_e32 v80, v80, v230
	v_add_f32_e32 v80, v80, v232
	v_add_f32_e32 v80, v80, v234
	ds_read_b128 v[196:199], v56 offset:8192
	ds_read_b128 v[200:203], v56 offset:9216
	ds_read_b128 v[204:207], v56 offset:10240
	ds_read_b128 v[208:211], v56 offset:11264
	s_waitcnt lgkmcnt(4)
	v_mul_f32_e32 v228, v29, v213
	v_mul_f32_e32 v229, v27, v215
	v_mul_f32_e32 v230, v33, v217
	v_mul_f32_e32 v231, v31, v219
	v_mul_f32_e32 v232, v41, v221
	v_mul_f32_e32 v233, v39, v223
	v_mul_f32_e32 v234, v37, v225
	v_mul_f32_e32 v235, v35, v227
	v_fmac_f32_e32 v228, v28, v212
	v_fmac_f32_e32 v229, v26, v214
	v_fmac_f32_e32 v230, v32, v216
	v_fmac_f32_e32 v231, v30, v218
	v_fmac_f32_e32 v232, v40, v220
	v_fmac_f32_e32 v233, v38, v222
	v_fmac_f32_e32 v234, v36, v224
	v_fmac_f32_e32 v235, v34, v226
	v_add_f32_e32 v228, v228, v229
	v_add_f32_e32 v230, v230, v231
	v_add_f32_e32 v232, v232, v233
	v_add_f32_e32 v234, v234, v235
	v_add_f32_e32 v81, 0, v228
	v_add_f32_e32 v81, v81, v230
	v_add_f32_e32 v81, v81, v232
	v_add_f32_e32 v81, v81, v234
	ds_read_b128 v[212:215], v56 offset:12288
	ds_read_b128 v[216:219], v56 offset:13312
	ds_read_b128 v[220:223], v56 offset:14336
	ds_read_b128 v[224:227], v56 offset:15360
	s_waitcnt lgkmcnt(4)
	v_mul_f32_e32 v228, v29, v197
	v_mul_f32_e32 v229, v27, v199
	v_mul_f32_e32 v230, v33, v201
	v_mul_f32_e32 v231, v31, v203
	v_mul_f32_e32 v232, v41, v205
	v_mul_f32_e32 v233, v39, v207
	v_mul_f32_e32 v234, v37, v209
	v_mul_f32_e32 v235, v35, v211
	v_fmac_f32_e32 v228, v28, v196
	v_fmac_f32_e32 v229, v26, v198
	v_fmac_f32_e32 v230, v32, v200
	v_fmac_f32_e32 v231, v30, v202
	v_fmac_f32_e32 v232, v40, v204
	v_fmac_f32_e32 v233, v38, v206
	v_fmac_f32_e32 v234, v36, v208
	v_fmac_f32_e32 v235, v34, v210
	v_add_f32_e32 v228, v228, v229
	v_add_f32_e32 v230, v230, v231
	v_add_f32_e32 v232, v232, v233
	v_add_f32_e32 v234, v234, v235
	v_add_f32_e32 v82, 0, v228
	v_add_f32_e32 v82, v82, v230
	v_add_f32_e32 v82, v82, v232
	v_add_f32_e32 v82, v82, v234
	ds_read_b128 v[196:199], v56 offset:16384
	ds_read_b128 v[200:203], v56 offset:17408
	ds_read_b128 v[204:207], v56 offset:18432
	ds_read_b128 v[208:211], v56 offset:19456
	s_waitcnt lgkmcnt(4)
	v_mul_f32_e32 v228, v29, v213
	v_mul_f32_e32 v229, v27, v215
	v_mul_f32_e32 v230, v33, v217
	v_mul_f32_e32 v231, v31, v219
	v_mul_f32_e32 v232, v41, v221
	v_mul_f32_e32 v233, v39, v223
	v_mul_f32_e32 v234, v37, v225
	v_mul_f32_e32 v235, v35, v227
	v_fmac_f32_e32 v228, v28, v212
	v_fmac_f32_e32 v229, v26, v214
	v_fmac_f32_e32 v230, v32, v216
	v_fmac_f32_e32 v231, v30, v218
	v_fmac_f32_e32 v232, v40, v220
	v_fmac_f32_e32 v233, v38, v222
	v_fmac_f32_e32 v234, v36, v224
	v_fmac_f32_e32 v235, v34, v226
	v_add_f32_e32 v228, v228, v229
	v_add_f32_e32 v230, v230, v231
	v_add_f32_e32 v232, v232, v233
	v_add_f32_e32 v234, v234, v235
	v_add_f32_e32 v83, 0, v228
	v_add_f32_e32 v83, v83, v230
	v_add_f32_e32 v83, v83, v232
	v_add_f32_e32 v83, v83, v234
	ds_read_b128 v[212:215], v56 offset:20480
	ds_read_b128 v[216:219], v56 offset:21504
	ds_read_b128 v[220:223], v56 offset:22528
	ds_read_b128 v[224:227], v56 offset:23552
	s_waitcnt lgkmcnt(4)
	v_mul_f32_e32 v228, v29, v197
	v_mul_f32_e32 v229, v27, v199
	v_mul_f32_e32 v230, v33, v201
	v_mul_f32_e32 v231, v31, v203
	v_mul_f32_e32 v232, v41, v205
	v_mul_f32_e32 v233, v39, v207
	v_mul_f32_e32 v234, v37, v209
	v_mul_f32_e32 v235, v35, v211
	v_fmac_f32_e32 v228, v28, v196
	v_fmac_f32_e32 v229, v26, v198
	v_fmac_f32_e32 v230, v32, v200
	v_fmac_f32_e32 v231, v30, v202
	v_fmac_f32_e32 v232, v40, v204
	v_fmac_f32_e32 v233, v38, v206
	v_fmac_f32_e32 v234, v36, v208
	v_fmac_f32_e32 v235, v34, v210
	v_add_f32_e32 v228, v228, v229
	v_add_f32_e32 v230, v230, v231
	v_add_f32_e32 v232, v232, v233
	v_add_f32_e32 v234, v234, v235
	v_add_f32_e32 v84, 0, v228
	v_add_f32_e32 v84, v84, v230
	v_add_f32_e32 v84, v84, v232
	v_add_f32_e32 v84, v84, v234
	ds_read_b128 v[196:199], v56 offset:24576
	ds_read_b128 v[200:203], v56 offset:25600
	ds_read_b128 v[204:207], v56 offset:26624
	ds_read_b128 v[208:211], v56 offset:27648
	s_waitcnt lgkmcnt(4)
	v_mul_f32_e32 v228, v29, v213
	v_mul_f32_e32 v229, v27, v215
	v_mul_f32_e32 v230, v33, v217
	v_mul_f32_e32 v231, v31, v219
	v_mul_f32_e32 v232, v41, v221
	v_mul_f32_e32 v233, v39, v223
	v_mul_f32_e32 v234, v37, v225
	v_mul_f32_e32 v235, v35, v227
	v_fmac_f32_e32 v228, v28, v212
	v_fmac_f32_e32 v229, v26, v214
	v_fmac_f32_e32 v230, v32, v216
	v_fmac_f32_e32 v231, v30, v218
	v_fmac_f32_e32 v232, v40, v220
	v_fmac_f32_e32 v233, v38, v222
	v_fmac_f32_e32 v234, v36, v224
	v_fmac_f32_e32 v235, v34, v226
	v_add_f32_e32 v228, v228, v229
	v_add_f32_e32 v230, v230, v231
	v_add_f32_e32 v232, v232, v233
	v_add_f32_e32 v234, v234, v235
	v_add_f32_e32 v85, 0, v228
	v_add_f32_e32 v85, v85, v230
	v_add_f32_e32 v85, v85, v232
	v_add_f32_e32 v85, v85, v234
	ds_read_b128 v[212:215], v56 offset:28672
	ds_read_b128 v[216:219], v56 offset:29696
	ds_read_b128 v[220:223], v56 offset:30720
	ds_read_b128 v[224:227], v56 offset:31744
	s_waitcnt lgkmcnt(4)
	v_mul_f32_e32 v228, v29, v197
	v_mul_f32_e32 v229, v27, v199
	v_mul_f32_e32 v230, v33, v201
	v_mul_f32_e32 v231, v31, v203
	v_mul_f32_e32 v232, v41, v205
	v_mul_f32_e32 v233, v39, v207
	v_mul_f32_e32 v234, v37, v209
	v_mul_f32_e32 v235, v35, v211
	v_fmac_f32_e32 v228, v28, v196
	v_fmac_f32_e32 v229, v26, v198
	v_fmac_f32_e32 v230, v32, v200
	v_fmac_f32_e32 v231, v30, v202
	v_fmac_f32_e32 v232, v40, v204
	v_fmac_f32_e32 v233, v38, v206
	v_fmac_f32_e32 v234, v36, v208
	v_fmac_f32_e32 v235, v34, v210
	v_add_f32_e32 v228, v228, v229
	v_add_f32_e32 v230, v230, v231
	v_add_f32_e32 v232, v232, v233
	v_add_f32_e32 v234, v234, v235
	v_add_f32_e32 v86, 0, v228
	v_add_f32_e32 v86, v86, v230
	v_add_f32_e32 v86, v86, v232
	v_add_f32_e32 v86, v86, v234
	ds_read_b128 v[196:199], v56 offset:32768
	ds_read_b128 v[200:203], v56 offset:33792
	ds_read_b128 v[204:207], v56 offset:34816
	ds_read_b128 v[208:211], v56 offset:35840
	s_waitcnt lgkmcnt(4)
	v_mul_f32_e32 v228, v29, v213
	v_mul_f32_e32 v229, v27, v215
	v_mul_f32_e32 v230, v33, v217
	v_mul_f32_e32 v231, v31, v219
	v_mul_f32_e32 v232, v41, v221
	v_mul_f32_e32 v233, v39, v223
	v_mul_f32_e32 v234, v37, v225
	v_mul_f32_e32 v235, v35, v227
	v_fmac_f32_e32 v228, v28, v212
	v_fmac_f32_e32 v229, v26, v214
	v_fmac_f32_e32 v230, v32, v216
	v_fmac_f32_e32 v231, v30, v218
	v_fmac_f32_e32 v232, v40, v220
	v_fmac_f32_e32 v233, v38, v222
	v_fmac_f32_e32 v234, v36, v224
	v_fmac_f32_e32 v235, v34, v226
	v_add_f32_e32 v228, v228, v229
	v_add_f32_e32 v230, v230, v231
	v_add_f32_e32 v232, v232, v233
	v_add_f32_e32 v234, v234, v235
	v_add_f32_e32 v87, 0, v228
	v_add_f32_e32 v87, v87, v230
	v_add_f32_e32 v87, v87, v232
	v_add_f32_e32 v87, v87, v234
	ds_read_b128 v[212:215], v56 offset:36864
	ds_read_b128 v[216:219], v56 offset:37888
	ds_read_b128 v[220:223], v56 offset:38912
	ds_read_b128 v[224:227], v56 offset:39936
	s_waitcnt lgkmcnt(4)
	v_mul_f32_e32 v228, v29, v197
	v_mul_f32_e32 v229, v27, v199
	v_mul_f32_e32 v230, v33, v201
	v_mul_f32_e32 v231, v31, v203
	v_mul_f32_e32 v232, v41, v205
	v_mul_f32_e32 v233, v39, v207
	v_mul_f32_e32 v234, v37, v209
	v_mul_f32_e32 v235, v35, v211
	v_fmac_f32_e32 v228, v28, v196
	v_fmac_f32_e32 v229, v26, v198
	v_fmac_f32_e32 v230, v32, v200
	v_fmac_f32_e32 v231, v30, v202
	v_fmac_f32_e32 v232, v40, v204
	v_fmac_f32_e32 v233, v38, v206
	v_fmac_f32_e32 v234, v36, v208
	v_fmac_f32_e32 v235, v34, v210
	v_add_f32_e32 v228, v228, v229
	v_add_f32_e32 v230, v230, v231
	v_add_f32_e32 v232, v232, v233
	v_add_f32_e32 v234, v234, v235
	v_add_f32_e32 v88, 0, v228
	v_add_f32_e32 v88, v88, v230
	v_add_f32_e32 v88, v88, v232
	v_add_f32_e32 v88, v88, v234
	ds_read_b128 v[196:199], v56 offset:40960
	ds_read_b128 v[200:203], v56 offset:41984
	ds_read_b128 v[204:207], v56 offset:43008
	ds_read_b128 v[208:211], v56 offset:44032
	s_waitcnt lgkmcnt(4)
	v_mul_f32_e32 v228, v29, v213
	v_mul_f32_e32 v229, v27, v215
	v_mul_f32_e32 v230, v33, v217
	v_mul_f32_e32 v231, v31, v219
	v_mul_f32_e32 v232, v41, v221
	v_mul_f32_e32 v233, v39, v223
	v_mul_f32_e32 v234, v37, v225
	v_mul_f32_e32 v235, v35, v227
	v_fmac_f32_e32 v228, v28, v212
	v_fmac_f32_e32 v229, v26, v214
	v_fmac_f32_e32 v230, v32, v216
	v_fmac_f32_e32 v231, v30, v218
	v_fmac_f32_e32 v232, v40, v220
	v_fmac_f32_e32 v233, v38, v222
	v_fmac_f32_e32 v234, v36, v224
	v_fmac_f32_e32 v235, v34, v226
	v_add_f32_e32 v228, v228, v229
	v_add_f32_e32 v230, v230, v231
	v_add_f32_e32 v232, v232, v233
	v_add_f32_e32 v234, v234, v235
	v_add_f32_e32 v89, 0, v228
	v_add_f32_e32 v89, v89, v230
	v_add_f32_e32 v89, v89, v232
	v_add_f32_e32 v89, v89, v234
	ds_read_b128 v[212:215], v56 offset:45056
	ds_read_b128 v[216:219], v56 offset:46080
	ds_read_b128 v[220:223], v56 offset:47104
	ds_read_b128 v[224:227], v56 offset:48128
	s_waitcnt lgkmcnt(4)
	v_mul_f32_e32 v228, v29, v197
	v_mul_f32_e32 v229, v27, v199
	v_mul_f32_e32 v230, v33, v201
	v_mul_f32_e32 v231, v31, v203
	v_mul_f32_e32 v232, v41, v205
	v_mul_f32_e32 v233, v39, v207
	v_mul_f32_e32 v234, v37, v209
	v_mul_f32_e32 v235, v35, v211
	v_fmac_f32_e32 v228, v28, v196
	v_fmac_f32_e32 v229, v26, v198
	v_fmac_f32_e32 v230, v32, v200
	v_fmac_f32_e32 v231, v30, v202
	v_fmac_f32_e32 v232, v40, v204
	v_fmac_f32_e32 v233, v38, v206
	v_fmac_f32_e32 v234, v36, v208
	v_fmac_f32_e32 v235, v34, v210
	v_add_f32_e32 v228, v228, v229
	v_add_f32_e32 v230, v230, v231
	v_add_f32_e32 v232, v232, v233
	v_add_f32_e32 v234, v234, v235
	v_add_f32_e32 v90, 0, v228
	v_add_f32_e32 v90, v90, v230
	v_add_f32_e32 v90, v90, v232
	v_add_f32_e32 v90, v90, v234
	ds_read_b128 v[196:199], v56 offset:49152
	ds_read_b128 v[200:203], v56 offset:50176
	ds_read_b128 v[204:207], v56 offset:51200
	ds_read_b128 v[208:211], v56 offset:52224
	s_waitcnt lgkmcnt(4)
	v_mul_f32_e32 v228, v29, v213
	v_mul_f32_e32 v229, v27, v215
	v_mul_f32_e32 v230, v33, v217
	v_mul_f32_e32 v231, v31, v219
	v_mul_f32_e32 v232, v41, v221
	v_mul_f32_e32 v233, v39, v223
	v_mul_f32_e32 v234, v37, v225
	v_mul_f32_e32 v235, v35, v227
	v_fmac_f32_e32 v228, v28, v212
	v_fmac_f32_e32 v229, v26, v214
	v_fmac_f32_e32 v230, v32, v216
	v_fmac_f32_e32 v231, v30, v218
	v_fmac_f32_e32 v232, v40, v220
	v_fmac_f32_e32 v233, v38, v222
	v_fmac_f32_e32 v234, v36, v224
	v_fmac_f32_e32 v235, v34, v226
	v_add_f32_e32 v228, v228, v229
	v_add_f32_e32 v230, v230, v231
	v_add_f32_e32 v232, v232, v233
	v_add_f32_e32 v234, v234, v235
	v_add_f32_e32 v91, 0, v228
	v_add_f32_e32 v91, v91, v230
	v_add_f32_e32 v91, v91, v232
	v_add_f32_e32 v91, v91, v234
	ds_read_b128 v[212:215], v56 offset:53248
	ds_read_b128 v[216:219], v56 offset:54272
	ds_read_b128 v[220:223], v56 offset:55296
	ds_read_b128 v[224:227], v56 offset:56320
	s_waitcnt lgkmcnt(4)
	v_mul_f32_e32 v228, v29, v197
	v_mul_f32_e32 v229, v27, v199
	v_mul_f32_e32 v230, v33, v201
	v_mul_f32_e32 v231, v31, v203
	v_mul_f32_e32 v232, v41, v205
	v_mul_f32_e32 v233, v39, v207
	v_mul_f32_e32 v234, v37, v209
	v_mul_f32_e32 v235, v35, v211
	v_fmac_f32_e32 v228, v28, v196
	v_fmac_f32_e32 v229, v26, v198
	v_fmac_f32_e32 v230, v32, v200
	v_fmac_f32_e32 v231, v30, v202
	v_fmac_f32_e32 v232, v40, v204
	v_fmac_f32_e32 v233, v38, v206
	v_fmac_f32_e32 v234, v36, v208
	v_fmac_f32_e32 v235, v34, v210
	v_add_f32_e32 v228, v228, v229
	v_add_f32_e32 v230, v230, v231
	v_add_f32_e32 v232, v232, v233
	v_add_f32_e32 v234, v234, v235
	v_add_f32_e32 v92, 0, v228
	v_add_f32_e32 v92, v92, v230
	v_add_f32_e32 v92, v92, v232
	v_add_f32_e32 v92, v92, v234
	ds_read_b128 v[196:199], v56 offset:57344
	ds_read_b128 v[200:203], v56 offset:58368
	ds_read_b128 v[204:207], v56 offset:59392
	ds_read_b128 v[208:211], v56 offset:60416
	s_waitcnt lgkmcnt(4)
	v_mul_f32_e32 v228, v29, v213
	v_mul_f32_e32 v229, v27, v215
	v_mul_f32_e32 v230, v33, v217
	v_mul_f32_e32 v231, v31, v219
	v_mul_f32_e32 v232, v41, v221
	v_mul_f32_e32 v233, v39, v223
	v_mul_f32_e32 v234, v37, v225
	v_mul_f32_e32 v235, v35, v227
	v_fmac_f32_e32 v228, v28, v212
	v_fmac_f32_e32 v229, v26, v214
	v_fmac_f32_e32 v230, v32, v216
	v_fmac_f32_e32 v231, v30, v218
	v_fmac_f32_e32 v232, v40, v220
	v_fmac_f32_e32 v233, v38, v222
	v_fmac_f32_e32 v234, v36, v224
	v_fmac_f32_e32 v235, v34, v226
	v_add_f32_e32 v228, v228, v229
	v_add_f32_e32 v230, v230, v231
	v_add_f32_e32 v232, v232, v233
	v_add_f32_e32 v234, v234, v235
	v_add_f32_e32 v93, 0, v228
	v_add_f32_e32 v93, v93, v230
	v_add_f32_e32 v93, v93, v232
	v_add_f32_e32 v93, v93, v234
	ds_read_b128 v[212:215], v56 offset:61440
	ds_read_b128 v[216:219], v56 offset:62464
	ds_read_b128 v[220:223], v56 offset:63488
	ds_read_b128 v[224:227], v56 offset:64512
	s_waitcnt lgkmcnt(4)
	v_mul_f32_e32 v228, v29, v197
	v_mul_f32_e32 v229, v27, v199
	v_mul_f32_e32 v230, v33, v201
	v_mul_f32_e32 v231, v31, v203
	v_mul_f32_e32 v232, v41, v205
	v_mul_f32_e32 v233, v39, v207
	v_mul_f32_e32 v234, v37, v209
	v_mul_f32_e32 v235, v35, v211
	v_fmac_f32_e32 v228, v28, v196
	v_fmac_f32_e32 v229, v26, v198
	v_fmac_f32_e32 v230, v32, v200
	v_fmac_f32_e32 v231, v30, v202
	v_fmac_f32_e32 v232, v40, v204
	v_fmac_f32_e32 v233, v38, v206
	v_fmac_f32_e32 v234, v36, v208
	v_fmac_f32_e32 v235, v34, v210
	v_add_f32_e32 v228, v228, v229
	v_add_f32_e32 v230, v230, v231
	v_add_f32_e32 v232, v232, v233
	v_add_f32_e32 v234, v234, v235
	v_add_f32_e32 v94, 0, v228
	v_add_f32_e32 v94, v94, v230
	v_add_f32_e32 v94, v94, v232
	v_add_f32_e32 v94, v94, v234
	s_waitcnt lgkmcnt(0)
	v_mul_f32_e32 v228, v29, v213
	v_mul_f32_e32 v229, v27, v215
	v_mul_f32_e32 v230, v33, v217
	v_mul_f32_e32 v231, v31, v219
	v_mul_f32_e32 v232, v41, v221
	v_mul_f32_e32 v233, v39, v223
	v_mul_f32_e32 v234, v37, v225
	v_mul_f32_e32 v235, v35, v227
	v_fmac_f32_e32 v228, v28, v212
	v_fmac_f32_e32 v229, v26, v214
	v_fmac_f32_e32 v230, v32, v216
	v_fmac_f32_e32 v231, v30, v218
	v_fmac_f32_e32 v232, v40, v220
	v_fmac_f32_e32 v233, v38, v222
	v_fmac_f32_e32 v234, v36, v224
	v_fmac_f32_e32 v235, v34, v226
	v_add_f32_e32 v228, v228, v229
	v_add_f32_e32 v230, v230, v231
	v_add_f32_e32 v232, v232, v233
	v_add_f32_e32 v234, v234, v235
	v_add_f32_e32 v95, 0, v228
	v_add_f32_e32 v95, v95, v230
	v_add_f32_e32 v95, v95, v232
	v_add_f32_e32 v95, v95, v234
	v_permlane32_swap_b32_e32 v80, v88
	v_permlane32_swap_b32_e32 v81, v89
	v_permlane32_swap_b32_e32 v82, v90
	v_permlane32_swap_b32_e32 v83, v91
	v_permlane32_swap_b32_e32 v84, v92
	v_permlane32_swap_b32_e32 v85, v93
	v_permlane32_swap_b32_e32 v86, v94
	v_permlane32_swap_b32_e32 v87, v95
	v_add_f32_e32 v80, v80, v88
	v_add_f32_e32 v81, v81, v89
	v_add_f32_e32 v82, v82, v90
	v_add_f32_e32 v83, v83, v91
	v_add_f32_e32 v84, v84, v92
	v_add_f32_e32 v85, v85, v93
	v_add_f32_e32 v86, v86, v94
	v_add_f32_e32 v87, v87, v95
	s_mov_b32 vcc_lo, 0xffff0000
	s_mov_b32 vcc_hi, 0xffff0000
	v_cndmask_b32_e32 v240, v84, v80, vcc
	v_cndmask_b32_e32 v241, v85, v81, vcc
	v_cndmask_b32_e32 v242, v86, v82, vcc
	v_cndmask_b32_e32 v243, v87, v83, vcc
	v_cndmask_b32_e32 v236, v80, v84, vcc
	v_cndmask_b32_e32 v237, v81, v85, vcc
	v_cndmask_b32_e32 v238, v82, v86, vcc
	v_cndmask_b32_e32 v239, v83, v87, vcc
	ds_swizzle_b32 v232, v240 offset:swizzle(SWAP,16)
	ds_swizzle_b32 v233, v241 offset:swizzle(SWAP,16)
	ds_swizzle_b32 v234, v242 offset:swizzle(SWAP,16)
	ds_swizzle_b32 v235, v243 offset:swizzle(SWAP,16)
	s_waitcnt lgkmcnt(0)
	v_add_f32_e32 v88, v236, v232
	v_add_f32_e32 v89, v237, v233
	v_add_f32_e32 v90, v238, v234
	v_add_f32_e32 v91, v239, v235
	v_add_f32_dpp v88, v88, v88 row_ror:8 row_mask:0xf bank_mask:0xf
	v_add_f32_dpp v89, v89, v89 row_ror:8 row_mask:0xf bank_mask:0xf
	v_add_f32_dpp v90, v90, v90 row_ror:8 row_mask:0xf bank_mask:0xf
	v_add_f32_dpp v91, v91, v91 row_ror:8 row_mask:0xf bank_mask:0xf
	v_add_f32_dpp v88, v88, v88 row_ror:4 row_mask:0xf bank_mask:0xf
	v_add_f32_dpp v89, v89, v89 row_ror:4 row_mask:0xf bank_mask:0xf
	v_add_f32_dpp v90, v90, v90 row_ror:4 row_mask:0xf bank_mask:0xf
	v_add_f32_dpp v91, v91, v91 row_ror:4 row_mask:0xf bank_mask:0xf
	v_add_f32_dpp v88, v88, v88 quad_perm:[2,3,0,1] row_mask:0xf bank_mask:0xf
	v_add_f32_dpp v89, v89, v89 quad_perm:[2,3,0,1] row_mask:0xf bank_mask:0xf
	v_add_f32_dpp v90, v90, v90 quad_perm:[2,3,0,1] row_mask:0xf bank_mask:0xf
	v_add_f32_dpp v91, v91, v91 quad_perm:[2,3,0,1] row_mask:0xf bank_mask:0xf
	v_add_f32_dpp v88, v88, v88 quad_perm:[1,0,3,2] row_mask:0xf bank_mask:0xf
	v_add_f32_dpp v89, v89, v89 quad_perm:[1,0,3,2] row_mask:0xf bank_mask:0xf
	v_add_f32_dpp v90, v90, v90 quad_perm:[1,0,3,2] row_mask:0xf bank_mask:0xf
	v_add_f32_dpp v91, v91, v91 quad_perm:[1,0,3,2] row_mask:0xf bank_mask:0xf
	s_mov_b32 vcc_lo, 0xaaaaaaaa
	s_mov_b32 vcc_hi, 0xaaaaaaaa
	v_cndmask_b32_e32 v92, v88, v89, vcc
	v_cndmask_b32_e32 v93, v90, v91, vcc
	s_mov_b32 vcc_lo, 0xcccccccc
	s_mov_b32 vcc_hi, 0xcccccccc
	v_cndmask_b32_e32 v92, v92, v93, vcc
	ds_bpermute_b32 v26, v97, v92
	s_waitcnt lgkmcnt(0)
	s_and_saveexec_b64 s[0:1], s[4:5]
	s_cbranch_execz .LBB0_693
	s_mov_b32 s2, 0xbfb8aa3b
	v_add_f32_e32 v26, v26, v99
	v_mul_f32_e64 v27, |v26|, s2
	v_exp_f32_e32 v27, v27
	v_min_f32_e32 v26, 0, v26
	v_add_f32_e32 v27, 1.0, v27
	v_log_f32_e32 v27, v27
	s_nop 0
	v_fmac_f32_e32 v26, 0xbf317218, v27
	global_store_dword v[16:17], v26, off
	s_branch .LBB0_693

.Lmy_nm_noreload:
	v_mul_f32_e32 v0, v31, v31
	v_mul_f32_e32 v60, v33, v33
	v_mul_f32_e32 v61, v11, v11
	v_mul_f32_e32 v62, v13, v13
	v_mul_f32_e32 v63, v7, v7
	v_mul_f32_e32 v64, v9, v9
	v_fmac_f32_e32 v0, v30, v30
	v_fmac_f32_e32 v60, v32, v32
	v_fmac_f32_e32 v61, v10, v10
	v_fmac_f32_e32 v62, v12, v12
	v_mul_f32_e32 v65, v3, v3
	v_mul_f32_e32 v66, v5, v5
	v_fmac_f32_e32 v63, v6, v6
	v_fmac_f32_e32 v64, v8, v8
	v_add_f32_e32 v0, v0, v60
	v_add_f32_e32 v60, v61, v62
	v_fmac_f32_e32 v65, v2, v2
	v_fmac_f32_e32 v66, v4, v4
	v_add_f32_e32 v61, v63, v64
	v_add_f32_e32 v0, v0, v60
	v_add_f32_e32 v62, v65, v66
	v_add_f32_e32 v0, v61, v0
	v_add_f32_e32 v0, v62, v0
	ds_swizzle_b32 v60, v0 offset:swizzle(SWAP,1)
	s_and_b64 vcc, exec, s[4:5]
	s_mov_b32 s6, s2
	s_waitcnt lgkmcnt(0)
	v_add_f32_e32 v0, v0, v60
	ds_swizzle_b32 v60, v0 offset:swizzle(SWAP,2)
	s_waitcnt lgkmcnt(0)
	v_add_f32_e32 v0, v0, v60
	ds_swizzle_b32 v60, v0 offset:swizzle(SWAP,4)
	s_waitcnt lgkmcnt(0)
	v_add_f32_e32 v0, v0, v60
	ds_swizzle_b32 v60, v0 offset:swizzle(SWAP,8)
	s_waitcnt lgkmcnt(0)
	v_add_f32_e32 v0, v0, v60
	v_mov_b32_e32 v60, v0
	s_nop 1
	v_permlane16_swap_b32_e32 v60, v0
	s_waitcnt lgkmcnt(0)
	v_add_f32_e32 v0, v0, v60
	v_mov_b32_e32 v60, v0
	s_nop 1
	v_permlane32_swap_b32_e32 v0, v60
	v_add_f32_e32 v0, v0, v60
	v_fmamk_f32 v0, v0, 0x3a800000, v244
	v_rsq_f32_e32 v0, v0
	s_nop 0
	v_pk_mul_f32 v[32:33], v[32:33], v[0:1] op_sel_hi:[1,0]
	v_pk_mul_f32 v[30:31], v[30:31], v[0:1] op_sel_hi:[1,0]
	v_pk_mul_f32 v[12:13], v[12:13], v[0:1] op_sel_hi:[1,0]
	v_pk_mul_f32 v[10:11], v[10:11], v[0:1] op_sel_hi:[1,0]
	v_pk_mul_f32 v[8:9], v[8:9], v[0:1] op_sel_hi:[1,0]
	v_pk_mul_f32 v[6:7], v[6:7], v[0:1] op_sel_hi:[1,0]
	v_mov_b64_e32 v[44:45], v[116:117]
	v_mov_b64_e32 v[46:47], v[118:119]
	v_pk_mul_f32 v[30:31], v[44:45], v[30:31]
	v_pk_mul_f32 v[32:33], v[46:47], v[32:33]
	v_mov_b64_e32 v[48:49], v[120:121]
	v_mov_b64_e32 v[50:51], v[122:123]
	v_pk_add_f32 v[46:47], v[48:49], 1.0 op_sel_hi:[1,0]
	v_pk_add_f32 v[44:45], v[50:51], 1.0 op_sel_hi:[1,0]
	v_mov_b64_e32 v[52:53], v[124:125]
	v_mov_b64_e32 v[54:55], v[126:127]
	v_pk_fma_f32 v[30:31], v[46:47], v[30:31], v[52:53]
	v_pk_fma_f32 v[32:33], v[44:45], v[32:33], v[54:55]
	v_cvt_pk_bf16_f32 v30, v30, v31
	s_nop 0
	v_cvt_pk_bf16_f32 v31, v32, v33
	global_store_dwordx2 v[42:43], v[30:31], off
	v_mov_b64_e32 v[30:31], v[80:81]
	v_mov_b64_e32 v[32:33], v[82:83]
	v_mov_b64_e32 v[44:45], v[84:85]
	v_mov_b64_e32 v[46:47], v[86:87]
	v_mov_b64_e32 v[48:49], v[88:89]
	v_mov_b64_e32 v[50:51], v[90:91]
	v_pk_mul_f32 v[10:11], v[30:31], v[10:11]
	v_pk_mul_f32 v[12:13], v[32:33], v[12:13]
	v_pk_add_f32 v[32:33], v[44:45], 1.0 op_sel_hi:[1,0]
	v_pk_add_f32 v[30:31], v[46:47], 1.0 op_sel_hi:[1,0]
	v_pk_fma_f32 v[10:11], v[32:33], v[10:11], v[48:49]
	v_pk_fma_f32 v[12:13], v[30:31], v[12:13], v[50:51]
	v_cvt_pk_bf16_f32 v10, v10, v11
	s_nop 0
	v_cvt_pk_bf16_f32 v11, v12, v13
	global_store_dwordx2 v[42:43], v[10:11], off offset:512
	s_waitcnt vmcnt(2)
	v_mov_b64_e32 v[10:11], v[92:93]
	v_mov_b64_e32 v[12:13], v[94:95]
	v_mov_b64_e32 v[30:31], v[96:97]
	v_mov_b64_e32 v[32:33], v[98:99]
	v_mov_b64_e32 v[44:45], v[100:101]
	v_mov_b64_e32 v[46:47], v[102:103]
	v_pk_mul_f32 v[6:7], v[6:7], v[10:11]
	v_pk_mul_f32 v[8:9], v[8:9], v[12:13]
	v_pk_add_f32 v[12:13], v[30:31], 1.0 op_sel_hi:[1,0]
	v_pk_add_f32 v[10:11], v[32:33], 1.0 op_sel_hi:[1,0]
	v_pk_fma_f32 v[6:7], v[6:7], v[12:13], v[44:45]
	v_pk_fma_f32 v[8:9], v[8:9], v[10:11], v[46:47]
	v_cvt_pk_bf16_f32 v6, v6, v7
	v_mov_b32_e32 v30, v14
	v_cvt_pk_bf16_f32 v7, v8, v9
	global_store_dwordx2 v[42:43], v[6:7], off offset:1024
	v_mov_b64_e32 v[44:45], v[104:105]
	v_mov_b64_e32 v[46:47], v[106:107]
	v_mov_b64_e32 v[48:49], v[108:109]
	v_mov_b64_e32 v[50:51], v[110:111]
	v_mov_b64_e32 v[52:53], v[112:113]
	v_mov_b64_e32 v[54:55], v[114:115]
	v_pk_mul_f32 v[58:59], v[2:3], v[0:1] op_sel_hi:[1,0]
	v_pk_mul_f32 v[56:57], v[4:5], v[0:1] op_sel_hi:[1,0]
	v_mov_b32_e32 v31, v15
	v_mov_b32_e32 v12, v20
	v_mov_b32_e32 v13, v21
	v_mov_b32_e32 v32, v16
	v_mov_b32_e32 v33, v17
	v_mov_b32_e32 v10, v18
	v_mov_b32_e32 v11, v19
	v_mov_b32_e32 v6, v22
	v_mov_b32_e32 v7, v23
	v_mov_b32_e32 v8, v24
	v_mov_b32_e32 v9, v25
	v_mov_b32_e32 v2, v26
	v_mov_b32_e32 v3, v27
	v_mov_b32_e32 v4, v28
	v_mov_b32_e32 v5, v29
	v_pk_mul_f32 v[14:15], v[58:59], v[44:45]
	v_pk_add_f32 v[20:21], v[48:49], 1.0 op_sel_hi:[1,0]
	v_pk_mul_f32 v[16:17], v[56:57], v[46:47]
	v_pk_add_f32 v[18:19], v[50:51], 1.0 op_sel_hi:[1,0]
	v_pk_fma_f32 v[14:15], v[14:15], v[20:21], v[52:53]
	v_pk_fma_f32 v[16:17], v[16:17], v[18:19], v[54:55]
	v_cvt_pk_bf16_f32 v14, v14, v15
	s_nop 0
	v_cvt_pk_bf16_f32 v15, v16, v17
	global_store_dwordx2 v[42:43], v[14:15], off offset:1536
	v_lshl_add_u64 v[42:43], v[42:43], 0, s[0:1]
	s_cbranch_vccnz .LBB0_707
